# MoBA tile loops rewritten as non-staggered interleaved loop: one barrier per tile, each wave mixes PV(i)+QK(i+2) MFMAs with evenly scheduled softmax VALU of tile i+1, ping-pong score registers (unroll
# speedup vs baseline: 1.0184x; 1.0015x over previous
; template <int MODE> __device__ __forceinline__ void attn_unit(int b, int h, int qb, int t_lo, const bf16_t* Q, const bf16_t* __restrict__ K, const bf16_t* __restrict__ V, bf16_t* O, ATT_LAS unsigned char* lds, const int wid, const float kn2, const float bmax) {
;     ...
;     const int grp = ATT_LOCKSTEP ? 2 : (wid >> 2);
;     asm volatile("s_waitcnt vmcnt(0) lgkmcnt(0)\n\ts_barrier" ::: "memory");
;     if (grp == 1) asm volatile("s_barrier" ::: "memory");
.LBB0_1058:
	s_nop 8
	v_exp_f32_e32 v56, v32
	s_nop 0
	v_exp_f32_e32 v57, v16
	v_exp_f32_e32 v112, v33
	v_exp_f32_e32 v16, v17
	v_exp_f32_e32 v58, v18
	v_add_f32_e32 v17, v57, v56
	v_exp_f32_e32 v18, v19
	v_pk_add_f32 v[32:33], v[16:17], v[112:113]
	v_exp_f32_e32 v17, v34
	v_pk_add_f32 v[32:33], v[32:33], v[32:33] op_sel_hi:[0,1]
	v_exp_f32_e32 v32, v35
	v_lshlrev_b32_e32 v59, 1, v52
	v_add_f32_e32 v19, v58, v17
	s_mov_b64 s[8:9], 0x80000
	v_pk_add_f32 v[34:35], v[18:19], v[32:33]
	v_exp_f32_e32 v19, v36
	v_pk_add_f32 v[34:35], v[34:35], v[34:35] op_sel_hi:[0,1]
	v_exp_f32_e32 v33, v20
	v_exp_f32_e32 v34, v37
	v_exp_f32_e32 v20, v21
	v_lshl_add_u64 v[114:115], v[48:49], 0, s[8:9]
	v_add_f32_e32 v21, v33, v19
	s_add_i32 s8, s86, s42
	v_pk_add_f32 v[36:37], v[20:21], v[34:35]
	v_exp_f32_e32 v21, v38
	v_pk_add_f32 v[36:37], v[36:37], v[36:37] op_sel_hi:[0,1]
	v_exp_f32_e32 v35, v22
	v_exp_f32_e32 v36, v39
	v_exp_f32_e32 v22, v23
	v_cvt_pk_bf16_f32 v100, v57, v16
	v_add_f32_e32 v23, v35, v21
	s_waitcnt vmcnt(0) lgkmcnt(0)
	s_barrier
	v_pk_add_f32 v[38:39], v[22:23], v[36:37]
	v_exp_f32_e32 v23, v40
	v_pk_add_f32 v[38:39], v[38:39], v[38:39] op_sel_hi:[0,1]
	v_exp_f32_e32 v37, v24
	v_exp_f32_e32 v38, v41
	v_exp_f32_e32 v24, v25
	v_and_b32_e32 v25, 32, v59
	v_add_u32_e32 v59, s89, v25
	v_add_f32_e32 v25, v37, v23
	v_pk_add_f32 v[40:41], v[24:25], v[38:39]
	v_exp_f32_e32 v25, v42
	v_pk_add_f32 v[40:41], v[40:41], v[40:41] op_sel_hi:[0,1]
	v_exp_f32_e32 v39, v26
	v_exp_f32_e32 v40, v43
	v_exp_f32_e32 v26, v27
	v_lshrrev_b32_e32 v27, 2, v52
	v_and_or_b32 v52, v27, 3, v55
	v_add_f32_e32 v27, v39, v25
	v_pk_add_f32 v[42:43], v[26:27], v[40:41]
	v_exp_f32_e32 v27, v44
	v_pk_add_f32 v[42:43], v[42:43], v[42:43] op_sel_hi:[0,1]
	v_exp_f32_e32 v41, v28
	v_exp_f32_e32 v42, v45
	v_exp_f32_e32 v28, v29
	v_add_u32_e32 v16, s8, v54
	v_add_f32_e32 v29, v41, v27
	s_lshl_b32 s30, s91, 2
	v_pk_add_f32 v[44:45], v[28:29], v[42:43]
	v_exp_f32_e32 v29, v46
	v_pk_add_f32 v[44:45], v[44:45], v[44:45] op_sel_hi:[0,1]
	v_exp_f32_e32 v43, v30
	v_exp_f32_e32 v44, v47
	v_exp_f32_e32 v30, v31
	v_lshlrev_b32_e32 v52, 6, v52
	v_add_f32_e32 v31, v43, v29
	v_cvt_pk_bf16_f32 v108, v56, v112
	v_pk_add_f32 v[46:47], v[30:31], v[44:45]
	v_sub_u32_e32 v112, v16, v55
	v_add_f32_e32 v31, v46, v47
	v_mov_b32_e32 v16, 0
	s_add_i32 s31, s30, -2
	s_mov_b32 s34, 1
	s_add_i32 s35, s30, 4
	v_add3_u32 v132, v59, v53, v52
	s_mov_b32 s44, 0
	v_add_f32_e32 v131, 0, v31
	v_cvt_pk_bf16_f32 v109, v17, v32
	v_cvt_pk_bf16_f32 v110, v19, v34
	v_cvt_pk_bf16_f32 v111, v21, v36
	v_cvt_pk_bf16_f32 v104, v23, v38
	v_cvt_pk_bf16_f32 v105, v25, v40
	v_cvt_pk_bf16_f32 v106, v27, v42
	v_cvt_pk_bf16_f32 v107, v29, v44
	v_cvt_pk_bf16_f32 v101, v58, v18
	v_cvt_pk_bf16_f32 v102, v33, v20
	v_cvt_pk_bf16_f32 v103, v35, v22
	v_cvt_pk_bf16_f32 v96, v37, v24
	v_cvt_pk_bf16_f32 v97, v39, v26
	v_cvt_pk_bf16_f32 v98, v41, v28
	v_cvt_pk_bf16_f32 v99, v43, v30
	s_or_b32 s36, s30, 2
	v_lshl_add_u64 v[116:117], v[50:51], 0, s[26:27]
	v_mov_b32_e32 v17, v16
	v_mov_b32_e32 v18, v16
	v_mov_b32_e32 v19, v16
	v_mov_b32_e32 v20, v16
	v_mov_b32_e32 v21, v16
	v_mov_b32_e32 v22, v16
	v_mov_b32_e32 v23, v16
	v_mov_b32_e32 v24, v16
	v_mov_b32_e32 v25, v16
	v_mov_b32_e32 v26, v16
	v_mov_b32_e32 v27, v16
	v_mov_b32_e32 v28, v16
	v_mov_b32_e32 v29, v16
	v_mov_b32_e32 v30, v16
	v_mov_b32_e32 v31, v16
	v_mov_b32_e32 v32, v16
	v_mov_b32_e32 v33, v16
	v_mov_b32_e32 v34, v16
	v_mov_b32_e32 v35, v16
	v_mov_b32_e32 v36, v16
	v_mov_b32_e32 v37, v16
	v_mov_b32_e32 v38, v16
	v_mov_b32_e32 v39, v16
	v_mov_b32_e32 v40, v16
	v_mov_b32_e32 v41, v16
	v_mov_b32_e32 v42, v16
	v_mov_b32_e32 v43, v16
	v_mov_b32_e32 v44, v16
	v_mov_b32_e32 v45, v16
	v_mov_b32_e32 v46, v16
	v_mov_b32_e32 v47, v16
	s_and_b64 vcc, exec, s[6:7]
	s_cbranch_vccz .Lmb1_al
	s_barrier
.Lmb1_al:
	s_add_i32 s37, s34, -1
	s_mov_b32 s43, 0
	s_cmp_ge_u32 s37, s30
	s_cbranch_scc1 .Lmb1_pK
	s_and_b32 s45, s44, 0x6000
	s_add_i32 s45, s45, s74
	s_mov_b32 s99, m0
	s_mov_b32 m0, s45
	s_nop 0
	global_load_lds_dwordx4 v[114:115], off
	s_mov_b32 m0, s99
.Lmb1_pK:
	s_add_i32 s45, s37, 3
	s_cmp_ge_u32 s45, s35
	s_cbranch_scc1 .Lmb1_pV
	s_add_i32 s45, s44, 0x6000
	s_and_b32 s45, s45, 0x6000
	s_add_i32 s45, s45, s75
	s_mov_b32 s99, m0
	s_mov_b32 m0, s45
	s_nop 0
	global_load_lds_dwordx4 v[116:117], off
	s_mov_b32 m0, s99
; #define ATT_LAS __attribute__((address_space(3)))
; #define ATT_MFMA(a, b, c) __builtin_amdgcn_mfma_f32_32x32x16_bf16((a), (b), (c), 0, 0, 0)
; __device__ __forceinline__ void qkt(f32x16& p0, f32x16& p1, lds_cptr kb, const bf16x8* qr, const f32x16& z) {
; #pragma unroll
;     for (int d0 = 0; d0 < 4; ++d0) {
;         const bf16x8 b0 = *(const ATT_LAS bf16x8*)(kb + d0 * 2048);
;         const bf16x8 b1 = *(const ATT_LAS bf16x8*)(kb + d0 * 2048 + 512);
;         if (d0 == 0) { p0 = ATT_MFMA(b0, qr[0], z); p1 = ATT_MFMA(b1, qr[0], z); }
;         else { p0 = ATT_MFMA(b0, qr[d0], p0); p1 = ATT_MFMA(b1, qr[d0], p1); } }
; }
.Lmb1_pV:
	v_lshl_add_u64 v[114:115], v[114:115], 0, s[22:23]
	v_lshl_add_u64 v[116:117], v[116:117], 0, s[22:23]
	s_add_i32 s42, s44, 0x2000
	s_and_b32 s45, s42, 0x6000
	v_add_u32_e32 v133, s45, v130
	ds_read_b128 v[154:157], v133
	ds_read_b128 v[158:161], v133 offset:512
	ds_read_b128 v[162:165], v133 offset:2048
	ds_read_b128 v[166:169], v133 offset:2560
	ds_read_b128 v[170:173], v133 offset:4096
	ds_read_b128 v[174:177], v133 offset:4608
	ds_read_b128 v[178:181], v133 offset:6144
	ds_read_b128 v[182:185], v133 offset:6656
	s_and_b32 s45, s44, 0x6000
	v_add_u32_e32 v218, s45, v132
	ds_read_b64_tr_b16 v[186:187], v218
	ds_read_b64_tr_b16 v[188:189], v218 offset:512
	ds_read_b64_tr_b16 v[190:191], v218 offset:1024
	ds_read_b64_tr_b16 v[192:193], v218 offset:1536
	ds_read_b64_tr_b16 v[194:195], v218 offset:2048
	ds_read_b64_tr_b16 v[196:197], v218 offset:2560
	ds_read_b64_tr_b16 v[198:199], v218 offset:3072
	ds_read_b64_tr_b16 v[200:201], v218 offset:3584
	ds_read_b64_tr_b16 v[202:203], v218 offset:4096
	ds_read_b64_tr_b16 v[204:205], v218 offset:4608
	ds_read_b64_tr_b16 v[206:207], v218 offset:5120
	ds_read_b64_tr_b16 v[208:209], v218 offset:5632
	ds_read_b64_tr_b16 v[210:211], v218 offset:6144
	ds_read_b64_tr_b16 v[212:213], v218 offset:6656
	ds_read_b64_tr_b16 v[214:215], v218 offset:7168
	ds_read_b64_tr_b16 v[216:217], v218 offset:7680
	s_lshr_b32 s45, s34, 2
	v_lshrrev_b32_e32 v219, s45, v129
	v_and_b32_e32 v219, 1, v219
	v_cmp_eq_u32_e32 vcc, 1, v219
	s_cmp_ge_i32 s34, s31
	s_nop 0
	v_cndmask_b32_e32 v219, v126, v128, vcc
	s_cselect_b64 vcc, 0, -1
	s_nop 1
	v_cndmask_b32_e32 v219, 0, v219, vcc
	v_add_f32_e32 v220, v0, v219
	v_add_f32_e32 v221, v1, v219
	v_add_f32_e32 v222, v2, v219
	v_add_f32_e32 v223, v3, v219
	v_add_f32_e32 v224, v4, v219
	v_add_f32_e32 v225, v5, v219
	v_add_f32_e32 v226, v6, v219
	v_add_f32_e32 v227, v7, v219
	v_add_f32_e32 v228, v8, v219
	v_add_f32_e32 v229, v9, v219
	v_add_f32_e32 v230, v10, v219
	v_add_f32_e32 v231, v11, v219
	v_add_f32_e32 v232, v12, v219
	v_add_f32_e32 v233, v13, v219
	v_add_f32_e32 v234, v14, v219
	v_add_f32_e32 v235, v15, v219
	s_add_i32 s98, s34, 1
	s_waitcnt lgkmcnt(15)
	v_mfma_f32_32x32x16_bf16 v[64:79], v[154:157], v[92:95], v[220:235]
	v_mfma_f32_32x32x16_bf16 v[48:63], v[158:161], v[92:95], v[220:235]
	s_waitcnt lgkmcnt(15)
	v_mfma_f32_32x32x16_bf16 v[64:79], v[162:165], v[88:91], v[64:79]
	v_mfma_f32_32x32x16_bf16 v[48:63], v[166:169], v[88:91], v[48:63]
	s_waitcnt lgkmcnt(15)
	v_mfma_f32_32x32x16_bf16 v[64:79], v[170:173], v[84:87], v[64:79]
	v_mfma_f32_32x32x16_bf16 v[48:63], v[174:177], v[84:87], v[48:63]
	s_waitcnt lgkmcnt(15)
	v_mfma_f32_32x32x16_bf16 v[64:79], v[178:181], v[80:83], v[64:79]
	v_mfma_f32_32x32x16_bf16 v[48:63], v[182:185], v[80:83], v[48:63]
	s_lshr_b32 s45, s98, 2
	v_lshrrev_b32_e32 v219, s45, v129
	v_and_b32_e32 v219, 1, v219
	v_cmp_eq_u32_e32 vcc, 1, v219
	s_cmp_ge_i32 s98, s31
	s_nop 0
	v_cndmask_b32_e32 v219, v126, v128, vcc
	s_cselect_b64 vcc, 0, -1
	s_nop 1
	v_cndmask_b32_e32 v219, 0, v219, vcc
	v_add_f32_e32 v220, v0, v219
	v_add_f32_e32 v221, v1, v219
	v_add_f32_e32 v222, v2, v219
	v_add_f32_e32 v223, v3, v219
	v_add_f32_e32 v224, v4, v219
	v_add_f32_e32 v225, v5, v219
	v_add_f32_e32 v226, v6, v219
	v_add_f32_e32 v227, v7, v219
	v_add_f32_e32 v228, v8, v219
	v_add_f32_e32 v229, v9, v219
	v_add_f32_e32 v230, v10, v219
	v_add_f32_e32 v231, v11, v219
	v_add_f32_e32 v232, v12, v219
	v_add_f32_e32 v233, v13, v219
	v_add_f32_e32 v234, v14, v219
	v_add_f32_e32 v235, v15, v219
	s_waitcnt lgkmcnt(0)
.LBB0_1059:
.LBB0_1060:
.LBB0_1062:
.Lmb1_A:
	s_barrier
	s_add_i32 s45, s37, 1
	s_cmp_ge_u32 s45, s30
	s_cbranch_scc1 .Lmb1_skKA
	s_add_i32 s45, s44, 0x2000
	s_and_b32 s45, s45, 0x6000
	s_add_i32 s45, s45, s74
	s_mov_b32 s99, m0
	s_mov_b32 m0, s45
	s_nop 0
	global_load_lds_dwordx4 v[114:115], off
	s_mov_b32 m0, s99
	s_mov_b32 s43, 1
.Lmb1_skKA:
	s_add_i32 s45, s37, 4
	s_cmp_ge_u32 s45, s35
	s_cbranch_scc1 .Lmb1_skVA
	s_and_b32 s45, s44, 0x6000
	s_add_i32 s45, s45, s75
	s_mov_b32 s99, m0
	s_mov_b32 m0, s45
	s_nop 0
	global_load_lds_dwordx4 v[116:117], off
	s_mov_b32 m0, s99
	s_add_i32 s43, s43, 1
; #define ATT_LAS __attribute__((address_space(3)))
; #define ATT_MFMA(a, b, c) __builtin_amdgcn_mfma_f32_32x32x16_bf16((a), (b), (c), 0, 0, 0)
; __device__ __forceinline__ void qkt(f32x16& p0, f32x16& p1, lds_cptr kb, const bf16x8* qr, const f32x16& z) {
; #pragma unroll
;     for (int d0 = 0; d0 < 4; ++d0) {
;         const bf16x8 b0 = *(const ATT_LAS bf16x8*)(kb + d0 * 2048);
;         const bf16x8 b1 = *(const ATT_LAS bf16x8*)(kb + d0 * 2048 + 512);
;         if (d0 == 0) { p0 = ATT_MFMA(b0, qr[0], z); p1 = ATT_MFMA(b1, qr[0], z); }
;         else { p0 = ATT_MFMA(b0, qr[d0], p0); p1 = ATT_MFMA(b1, qr[d0], p1); } }
; }
; __device__ __forceinline__ void pv(f32x16* o, int vb, bf16x8 pa0, bf16x8 pa1, bf16x8 pa2, bf16x8 pa3) {
; #pragma unroll
;     for (int d0 = 0; d0 < 2; ++d0) { s16x4 lo[4], hi[4];
; #pragma unroll
;         for (int ks = 0; ks < 4; ++ks) {
;             asm volatile("ds_read_b64_tr_b16 %0,%1 offset:%c2" : "=&v"(lo[ks]) : "v"(vb), "i"(d0 * 4096 + ks * 1024) : "memory");
;             asm volatile("ds_read_b64_tr_b16 %0,%1 offset:%c2" : "=&v"(hi[ks]) : "v"(vb), "i"(d0 * 4096 + ks * 1024 + 512) : "memory"); }
;         asm volatile("s_waitcnt lgkmcnt(0)" ::: "memory"); __builtin_amdgcn_sched_barrier(0);
;     ...
;         o[d0] = ATT_MFMA(pa0, ATT_PK(0), o[d0]);
;         o[d0] = ATT_MFMA(pa1, ATT_PK(1), o[d0]);
;         o[d0] = ATT_MFMA(pa2, ATT_PK(2), o[d0]);
;         o[d0] = ATT_MFMA(pa3, ATT_PK(3), o[d0]);
;     ...
;     }
; }
.Lmb1_skVA:
	s_add_i32 s42, s44, 0x2000
	s_add_i32 s98, s44, 0x4000
	s_and_b32 s45, s98, 0x6000
	v_add_u32_e32 v133, s45, v130
	ds_read_b128 v[154:157], v133
	ds_read_b128 v[158:161], v133 offset:512
	ds_read_b128 v[162:165], v133 offset:2048
	ds_read_b128 v[166:169], v133 offset:2560
	ds_read_b128 v[170:173], v133 offset:4096
	ds_read_b128 v[174:177], v133 offset:4608
	ds_read_b128 v[178:181], v133 offset:6144
	ds_read_b128 v[182:185], v133 offset:6656
	s_and_b32 s45, s42, 0x6000
	v_add_u32_e32 v218, s45, v132
	s_add_i32 s98, s34, 2
	s_cmp_ge_i32 s34, s31
	s_cbranch_scc1 .Lmb1_A_near
	v_mfma_f32_32x32x16_bf16 v[16:31], v[108:111], v[186:189], v[16:31]
	v_exp_f32_e32 v64, v64
	v_exp_f32_e32 v48, v48
	v_mfma_f32_32x32x16_bf16 v[16:31], v[104:107], v[190:193], v[16:31]
	v_exp_f32_e32 v65, v65
	v_exp_f32_e32 v49, v49
	v_add_f32_e32 v252, v64, v48
	v_mfma_f32_32x32x16_bf16 v[16:31], v[100:103], v[194:197], v[16:31]
	v_exp_f32_e32 v66, v66
	v_exp_f32_e32 v50, v50
	v_add_f32_e32 v253, v65, v49
	v_add_f32_e32 v252, v252, v253
	v_mfma_f32_32x32x16_bf16 v[16:31], v[96:99], v[198:201], v[16:31]
	v_exp_f32_e32 v67, v67
	v_exp_f32_e32 v51, v51
	v_add_f32_e32 v253, v66, v50
	v_add_f32_e32 v252, v252, v253
	v_mfma_f32_32x32x16_bf16 v[32:47], v[108:111], v[202:205], v[32:47]
	v_exp_f32_e32 v68, v68
	v_exp_f32_e32 v52, v52
	v_add_f32_e32 v253, v67, v51
	v_add_f32_e32 v252, v252, v253
	ds_read_b64_tr_b16 v[186:187], v218
	ds_read_b64_tr_b16 v[188:189], v218 offset:512
	v_mfma_f32_32x32x16_bf16 v[32:47], v[104:107], v[206:209], v[32:47]
	v_exp_f32_e32 v69, v69
	v_exp_f32_e32 v53, v53
	v_add_f32_e32 v253, v68, v52
	v_add_f32_e32 v252, v252, v253
	ds_read_b64_tr_b16 v[190:191], v218 offset:1024
	ds_read_b64_tr_b16 v[192:193], v218 offset:1536
	v_mfma_f32_32x32x16_bf16 v[32:47], v[100:103], v[210:213], v[32:47]
	v_exp_f32_e32 v70, v70
	v_exp_f32_e32 v54, v54
	v_add_f32_e32 v253, v69, v53
	v_add_f32_e32 v252, v252, v253
	ds_read_b64_tr_b16 v[194:195], v218 offset:2048
	ds_read_b64_tr_b16 v[196:197], v218 offset:2560
	v_mfma_f32_32x32x16_bf16 v[32:47], v[96:99], v[214:217], v[32:47]
	v_exp_f32_e32 v71, v71
	v_exp_f32_e32 v55, v55
	v_add_f32_e32 v253, v70, v54
	v_add_f32_e32 v252, v252, v253
	ds_read_b64_tr_b16 v[198:199], v218 offset:3072
	ds_read_b64_tr_b16 v[200:201], v218 offset:3584
	s_waitcnt lgkmcnt(8)
	v_mfma_f32_32x32x16_bf16 v[236:251], v[154:157], v[92:95], v[220:235]
	v_exp_f32_e32 v72, v72
	v_exp_f32_e32 v56, v56
	v_add_f32_e32 v253, v71, v55
	v_add_f32_e32 v252, v252, v253
	v_cvt_pk_bf16_f32 v108, v64, v65
	v_cvt_pk_bf16_f32 v100, v48, v49
	ds_read_b64_tr_b16 v[202:203], v218 offset:4096
	ds_read_b64_tr_b16 v[204:205], v218 offset:4608
	v_mfma_f32_32x32x16_bf16 v[134:149], v[158:161], v[92:95], v[220:235]
	v_exp_f32_e32 v73, v73
	v_exp_f32_e32 v57, v57
	v_add_f32_e32 v253, v72, v56
	v_add_f32_e32 v252, v252, v253
	v_cvt_pk_bf16_f32 v109, v66, v67
	v_cvt_pk_bf16_f32 v101, v50, v51
	ds_read_b64_tr_b16 v[206:207], v218 offset:5120
	ds_read_b64_tr_b16 v[208:209], v218 offset:5632
	v_mfma_f32_32x32x16_bf16 v[236:251], v[162:165], v[88:91], v[236:251]
	v_exp_f32_e32 v74, v74
	v_exp_f32_e32 v58, v58
	v_add_f32_e32 v253, v73, v57
	v_add_f32_e32 v252, v252, v253
	v_cvt_pk_bf16_f32 v110, v68, v69
	v_cvt_pk_bf16_f32 v102, v52, v53
	ds_read_b64_tr_b16 v[210:211], v218 offset:6144
	ds_read_b64_tr_b16 v[212:213], v218 offset:6656
	v_mfma_f32_32x32x16_bf16 v[134:149], v[166:169], v[88:91], v[134:149]
	v_exp_f32_e32 v75, v75
	v_exp_f32_e32 v59, v59
	v_add_f32_e32 v253, v74, v58
	v_add_f32_e32 v252, v252, v253
	v_cvt_pk_bf16_f32 v111, v70, v71
	v_cvt_pk_bf16_f32 v103, v54, v55
	ds_read_b64_tr_b16 v[214:215], v218 offset:7168
	ds_read_b64_tr_b16 v[216:217], v218 offset:7680
	v_mfma_f32_32x32x16_bf16 v[236:251], v[170:173], v[84:87], v[236:251]
	v_exp_f32_e32 v76, v76
	v_exp_f32_e32 v60, v60
	v_add_f32_e32 v253, v75, v59
	v_add_f32_e32 v252, v252, v253
	v_cvt_pk_bf16_f32 v104, v72, v73
	v_cvt_pk_bf16_f32 v96, v56, v57
	v_mfma_f32_32x32x16_bf16 v[134:149], v[174:177], v[84:87], v[134:149]
	v_exp_f32_e32 v77, v77
	v_exp_f32_e32 v61, v61
	v_add_f32_e32 v253, v76, v60
	v_add_f32_e32 v252, v252, v253
	v_cvt_pk_bf16_f32 v105, v74, v75
	v_cvt_pk_bf16_f32 v97, v58, v59
	v_mfma_f32_32x32x16_bf16 v[236:251], v[178:181], v[80:83], v[236:251]
	v_exp_f32_e32 v78, v78
	v_exp_f32_e32 v62, v62
	v_add_f32_e32 v253, v77, v61
	v_add_f32_e32 v252, v252, v253
	v_cvt_pk_bf16_f32 v106, v76, v77
	v_cvt_pk_bf16_f32 v98, v60, v61
	v_mfma_f32_32x32x16_bf16 v[134:149], v[182:185], v[80:83], v[134:149]
	v_exp_f32_e32 v79, v79
	v_exp_f32_e32 v63, v63
	v_add_f32_e32 v253, v78, v62
	v_add_f32_e32 v252, v252, v253
	v_add_f32_e32 v253, v79, v63
	v_add_f32_e32 v252, v252, v253
	v_cvt_pk_bf16_f32 v107, v78, v79
	v_cvt_pk_bf16_f32 v99, v62, v63
	v_add_f32_e32 v131, v131, v252
.Lmb1_A_tail:
	s_and_b32 s45, s98, 3
	s_cmp_eq_u32 s45, 0
	s_cbranch_scc1 .Lmb1_A_cin
	s_cmp_lg_u32 s98, s31
	s_cbranch_scc1 .Lmb1_A_nocin
.Lmb1_A_cin:
	s_lshr_b32 s45, s98, 2
	v_lshrrev_b32_e32 v219, s45, v129
	v_and_b32_e32 v219, 1, v219
	v_cmp_eq_u32_e32 vcc, 1, v219
	s_cmp_ge_i32 s98, s31
	s_nop 0
	v_cndmask_b32_e32 v219, v126, v128, vcc
	s_cselect_b64 vcc, 0, -1
	s_nop 1
	v_cndmask_b32_e32 v219, 0, v219, vcc
	v_add_f32_e32 v220, v0, v219
	v_add_f32_e32 v221, v1, v219
	v_add_f32_e32 v222, v2, v219
	v_add_f32_e32 v223, v3, v219
	v_add_f32_e32 v224, v4, v219
	v_add_f32_e32 v225, v5, v219
	v_add_f32_e32 v226, v6, v219
	v_add_f32_e32 v227, v7, v219
	v_add_f32_e32 v228, v8, v219
	v_add_f32_e32 v229, v9, v219
	v_add_f32_e32 v230, v10, v219
	v_add_f32_e32 v231, v11, v219
	v_add_f32_e32 v232, v12, v219
	v_add_f32_e32 v233, v13, v219
	v_add_f32_e32 v234, v14, v219
	v_add_f32_e32 v235, v15, v219
.Lmb1_A_nocin:
	v_lshl_add_u64 v[114:115], v[114:115], 0, s[22:23]
	v_subrev_u32_e32 v112, 64, v112
	v_lshl_add_u64 v[116:117], v[116:117], 0, s[22:23]
	s_add_i32 s34, s34, 1
	s_cmp_eq_u32 s43, 2
	s_cbranch_scc0 .Lmb1_A_wo
	s_waitcnt vmcnt(2) lgkmcnt(0)
.Lmb1_A_wd:
	s_cmp_lg_u32 s37, s36
	s_cbranch_scc0 .Lmb1_exitfix
	s_mov_b32 s44, s42
	s_add_i32 s37, s34, -1
	s_mov_b32 s43, 0
.Lmb1_B:
	s_barrier
	s_add_i32 s45, s37, 1
	s_cmp_ge_u32 s45, s30
	s_cbranch_scc1 .Lmb1_skKB
	s_add_i32 s45, s44, 0x2000
	s_and_b32 s45, s45, 0x6000
	s_add_i32 s45, s45, s74
	s_mov_b32 s99, m0
	s_mov_b32 m0, s45
	s_nop 0
	global_load_lds_dwordx4 v[114:115], off
	s_mov_b32 m0, s99
	s_mov_b32 s43, 1

; #define ATT_LAS __attribute__((address_space(3)))
; #define ATT_MFMA(a, b, c) __builtin_amdgcn_mfma_f32_32x32x16_bf16((a), (b), (c), 0, 0, 0)
; __device__ __forceinline__ void qkt(f32x16& p0, f32x16& p1, lds_cptr kb, const bf16x8* qr, const f32x16& z) {
; #pragma unroll
;     for (int d0 = 0; d0 < 4; ++d0) {
;         const bf16x8 b0 = *(const ATT_LAS bf16x8*)(kb + d0 * 2048);
;         const bf16x8 b1 = *(const ATT_LAS bf16x8*)(kb + d0 * 2048 + 512);
;         if (d0 == 0) { p0 = ATT_MFMA(b0, qr[0], z); p1 = ATT_MFMA(b1, qr[0], z); }
;         else { p0 = ATT_MFMA(b0, qr[d0], p0); p1 = ATT_MFMA(b1, qr[d0], p1); } }
; }
; __device__ __forceinline__ void pv(f32x16* o, int vb, bf16x8 pa0, bf16x8 pa1, bf16x8 pa2, bf16x8 pa3) {
; #pragma unroll
;     for (int d0 = 0; d0 < 2; ++d0) { s16x4 lo[4], hi[4];
; #pragma unroll
;         for (int ks = 0; ks < 4; ++ks) {
;             asm volatile("ds_read_b64_tr_b16 %0,%1 offset:%c2" : "=&v"(lo[ks]) : "v"(vb), "i"(d0 * 4096 + ks * 1024) : "memory");
;             asm volatile("ds_read_b64_tr_b16 %0,%1 offset:%c2" : "=&v"(hi[ks]) : "v"(vb), "i"(d0 * 4096 + ks * 1024 + 512) : "memory"); }
;         asm volatile("s_waitcnt lgkmcnt(0)" ::: "memory"); __builtin_amdgcn_sched_barrier(0);
;     ...
;         o[d0] = ATT_MFMA(pa0, ATT_PK(0), o[d0]);
;         o[d0] = ATT_MFMA(pa1, ATT_PK(1), o[d0]);
;         o[d0] = ATT_MFMA(pa2, ATT_PK(2), o[d0]);
;         o[d0] = ATT_MFMA(pa3, ATT_PK(3), o[d0]);
;     ...
;     }
; }
.Lmb1_skVB:
	s_add_i32 s42, s44, 0x2000
	s_add_i32 s98, s44, 0x4000
	s_and_b32 s45, s98, 0x6000
	v_add_u32_e32 v133, s45, v130
	ds_read_b128 v[154:157], v133
	ds_read_b128 v[158:161], v133 offset:512
	ds_read_b128 v[162:165], v133 offset:2048
	ds_read_b128 v[166:169], v133 offset:2560
	ds_read_b128 v[170:173], v133 offset:4096
	ds_read_b128 v[174:177], v133 offset:4608
	ds_read_b128 v[178:181], v133 offset:6144
	ds_read_b128 v[182:185], v133 offset:6656
	s_and_b32 s45, s42, 0x6000
	v_add_u32_e32 v218, s45, v132
	s_add_i32 s98, s34, 2
	s_cmp_ge_i32 s34, s31
	s_cbranch_scc1 .Lmb1_B_near
	v_mfma_f32_32x32x16_bf16 v[16:31], v[108:111], v[186:189], v[16:31]
	v_exp_f32_e32 v236, v236
	v_exp_f32_e32 v134, v134
	v_mfma_f32_32x32x16_bf16 v[16:31], v[104:107], v[190:193], v[16:31]
	v_exp_f32_e32 v237, v237
	v_exp_f32_e32 v135, v135
	v_add_f32_e32 v252, v236, v134
	v_mfma_f32_32x32x16_bf16 v[16:31], v[100:103], v[194:197], v[16:31]
	v_exp_f32_e32 v238, v238
	v_exp_f32_e32 v136, v136
	v_add_f32_e32 v253, v237, v135
	v_add_f32_e32 v252, v252, v253
	v_mfma_f32_32x32x16_bf16 v[16:31], v[96:99], v[198:201], v[16:31]
	v_exp_f32_e32 v239, v239
	v_exp_f32_e32 v137, v137
	v_add_f32_e32 v253, v238, v136
	v_add_f32_e32 v252, v252, v253
	v_mfma_f32_32x32x16_bf16 v[32:47], v[108:111], v[202:205], v[32:47]
	v_exp_f32_e32 v240, v240
	v_exp_f32_e32 v138, v138
	v_add_f32_e32 v253, v239, v137
	v_add_f32_e32 v252, v252, v253
	ds_read_b64_tr_b16 v[186:187], v218
	ds_read_b64_tr_b16 v[188:189], v218 offset:512
	v_mfma_f32_32x32x16_bf16 v[32:47], v[104:107], v[206:209], v[32:47]
	v_exp_f32_e32 v241, v241
	v_exp_f32_e32 v139, v139
	v_add_f32_e32 v253, v240, v138
	v_add_f32_e32 v252, v252, v253
	ds_read_b64_tr_b16 v[190:191], v218 offset:1024
	ds_read_b64_tr_b16 v[192:193], v218 offset:1536
	v_mfma_f32_32x32x16_bf16 v[32:47], v[100:103], v[210:213], v[32:47]
	v_exp_f32_e32 v242, v242
	v_exp_f32_e32 v140, v140
	v_add_f32_e32 v253, v241, v139
	v_add_f32_e32 v252, v252, v253
	ds_read_b64_tr_b16 v[194:195], v218 offset:2048
	ds_read_b64_tr_b16 v[196:197], v218 offset:2560
	v_mfma_f32_32x32x16_bf16 v[32:47], v[96:99], v[214:217], v[32:47]
	v_exp_f32_e32 v243, v243
	v_exp_f32_e32 v141, v141
	v_add_f32_e32 v253, v242, v140
	v_add_f32_e32 v252, v252, v253
	ds_read_b64_tr_b16 v[198:199], v218 offset:3072
	ds_read_b64_tr_b16 v[200:201], v218 offset:3584
	s_waitcnt lgkmcnt(8)
	v_mfma_f32_32x32x16_bf16 v[64:79], v[154:157], v[92:95], v[220:235]
	v_exp_f32_e32 v244, v244
	v_exp_f32_e32 v142, v142
	v_add_f32_e32 v253, v243, v141
	v_add_f32_e32 v252, v252, v253
	v_cvt_pk_bf16_f32 v108, v236, v237
	v_cvt_pk_bf16_f32 v100, v134, v135
	ds_read_b64_tr_b16 v[202:203], v218 offset:4096
	ds_read_b64_tr_b16 v[204:205], v218 offset:4608
	v_mfma_f32_32x32x16_bf16 v[48:63], v[158:161], v[92:95], v[220:235]
	v_exp_f32_e32 v245, v245
	v_exp_f32_e32 v143, v143
	v_add_f32_e32 v253, v244, v142
	v_add_f32_e32 v252, v252, v253
	v_cvt_pk_bf16_f32 v109, v238, v239
	v_cvt_pk_bf16_f32 v101, v136, v137
	ds_read_b64_tr_b16 v[206:207], v218 offset:5120
	ds_read_b64_tr_b16 v[208:209], v218 offset:5632
	v_mfma_f32_32x32x16_bf16 v[64:79], v[162:165], v[88:91], v[64:79]
	v_exp_f32_e32 v246, v246
	v_exp_f32_e32 v144, v144
	v_add_f32_e32 v253, v245, v143
	v_add_f32_e32 v252, v252, v253
	v_cvt_pk_bf16_f32 v110, v240, v241
	v_cvt_pk_bf16_f32 v102, v138, v139
	ds_read_b64_tr_b16 v[210:211], v218 offset:6144
	ds_read_b64_tr_b16 v[212:213], v218 offset:6656
	v_mfma_f32_32x32x16_bf16 v[48:63], v[166:169], v[88:91], v[48:63]
	v_exp_f32_e32 v247, v247
	v_exp_f32_e32 v145, v145
	v_add_f32_e32 v253, v246, v144
	v_add_f32_e32 v252, v252, v253
	v_cvt_pk_bf16_f32 v111, v242, v243
	v_cvt_pk_bf16_f32 v103, v140, v141
	ds_read_b64_tr_b16 v[214:215], v218 offset:7168
	ds_read_b64_tr_b16 v[216:217], v218 offset:7680
	v_mfma_f32_32x32x16_bf16 v[64:79], v[170:173], v[84:87], v[64:79]
	v_exp_f32_e32 v248, v248
	v_exp_f32_e32 v146, v146
	v_add_f32_e32 v253, v247, v145
	v_add_f32_e32 v252, v252, v253
	v_cvt_pk_bf16_f32 v104, v244, v245
	v_cvt_pk_bf16_f32 v96, v142, v143
	v_mfma_f32_32x32x16_bf16 v[48:63], v[174:177], v[84:87], v[48:63]
	v_exp_f32_e32 v249, v249
	v_exp_f32_e32 v147, v147
	v_add_f32_e32 v253, v248, v146
	v_add_f32_e32 v252, v252, v253
	v_cvt_pk_bf16_f32 v105, v246, v247
	v_cvt_pk_bf16_f32 v97, v144, v145
	v_mfma_f32_32x32x16_bf16 v[64:79], v[178:181], v[80:83], v[64:79]
	v_exp_f32_e32 v250, v250
	v_exp_f32_e32 v148, v148
	v_add_f32_e32 v253, v249, v147
	v_add_f32_e32 v252, v252, v253
	v_cvt_pk_bf16_f32 v106, v248, v249
	v_cvt_pk_bf16_f32 v98, v146, v147
	v_mfma_f32_32x32x16_bf16 v[48:63], v[182:185], v[80:83], v[48:63]
	v_exp_f32_e32 v251, v251
	v_exp_f32_e32 v149, v149
	v_add_f32_e32 v253, v250, v148
	v_add_f32_e32 v252, v252, v253
	v_add_f32_e32 v253, v251, v149
	v_add_f32_e32 v252, v252, v253
	v_cvt_pk_bf16_f32 v107, v250, v251
	v_cvt_pk_bf16_f32 v99, v148, v149
	v_add_f32_e32 v131, v131, v252

; #define ATT_LAS __attribute__((address_space(3)))
; #define ATT_MFMA(a, b, c) __builtin_amdgcn_mfma_f32_32x32x16_bf16((a), (b), (c), 0, 0, 0)
; __device__ __forceinline__ void qkt(f32x16& p0, f32x16& p1, lds_cptr kb, const bf16x8* qr, const f32x16& z) {
; #pragma unroll
;     for (int d0 = 0; d0 < 4; ++d0) {
;         const bf16x8 b0 = *(const ATT_LAS bf16x8*)(kb + d0 * 2048);
;         const bf16x8 b1 = *(const ATT_LAS bf16x8*)(kb + d0 * 2048 + 512);
;         if (d0 == 0) { p0 = ATT_MFMA(b0, qr[0], z); p1 = ATT_MFMA(b1, qr[0], z); }
;         else { p0 = ATT_MFMA(b0, qr[d0], p0); p1 = ATT_MFMA(b1, qr[d0], p1); } }
; }
; __device__ __forceinline__ void pv(f32x16* o, int vb, bf16x8 pa0, bf16x8 pa1, bf16x8 pa2, bf16x8 pa3) {
; #pragma unroll
;     for (int d0 = 0; d0 < 2; ++d0) { s16x4 lo[4], hi[4];
; #pragma unroll
;         for (int ks = 0; ks < 4; ++ks) {
;             asm volatile("ds_read_b64_tr_b16 %0,%1 offset:%c2" : "=&v"(lo[ks]) : "v"(vb), "i"(d0 * 4096 + ks * 1024) : "memory");
;             asm volatile("ds_read_b64_tr_b16 %0,%1 offset:%c2" : "=&v"(hi[ks]) : "v"(vb), "i"(d0 * 4096 + ks * 1024 + 512) : "memory"); }
;         asm volatile("s_waitcnt lgkmcnt(0)" ::: "memory"); __builtin_amdgcn_sched_barrier(0);
;     ...
;         o[d0] = ATT_MFMA(pa0, ATT_PK(0), o[d0]);
;         o[d0] = ATT_MFMA(pa1, ATT_PK(1), o[d0]);
;         o[d0] = ATT_MFMA(pa2, ATT_PK(2), o[d0]);
;         o[d0] = ATT_MFMA(pa3, ATT_PK(3), o[d0]);
;     ...
;     }
; }
.Lmb1_B_wd:
	s_cmp_lg_u32 s37, s36
	s_cbranch_scc0 .Lmb1_exitfix
	s_mov_b32 s44, s42
	s_add_i32 s37, s34, -1
	s_mov_b32 s43, 0
	s_branch .Lmb1_A
.Lmb1_A_near:
	s_waitcnt lgkmcnt(8)
	v_mfma_f32_32x32x16_bf16 v[16:31], v[108:111], v[186:189], v[16:31]
	v_mfma_f32_32x32x16_bf16 v[16:31], v[104:107], v[190:193], v[16:31]
	v_mfma_f32_32x32x16_bf16 v[16:31], v[100:103], v[194:197], v[16:31]
	v_mfma_f32_32x32x16_bf16 v[16:31], v[96:99], v[198:201], v[16:31]
	v_mfma_f32_32x32x16_bf16 v[32:47], v[108:111], v[202:205], v[32:47]
	v_mfma_f32_32x32x16_bf16 v[32:47], v[104:107], v[206:209], v[32:47]
	v_mfma_f32_32x32x16_bf16 v[32:47], v[100:103], v[210:213], v[32:47]
	v_mfma_f32_32x32x16_bf16 v[32:47], v[96:99], v[214:217], v[32:47]
	s_lshr_b32 s44, s34, 2
	s_cmp_eq_u32 s44, s91
	s_cselect_b64 s[8:9], -1, 0
	s_lshl_b32 s44, 1, s44
	v_and_b32_e32 v96, s44, v129
	v_cmp_ne_u32_e32 vcc, 0, v96
	s_or_b64 vcc, s[8:9], vcc
	s_nop 0
	v_cndmask_b32_e32 v96, v127, v112, vcc
	v_lshl_add_u32 v96, v96, 2, 0
	v_add_u32_e32 v104, 0x1d000, v96
	ds_read2_b32 v[96:97], v104 offset0:58 offset1:59
	ds_read2_b32 v[98:99], v104 offset0:26 offset1:27
	ds_read2_b32 v[100:101], v104 offset0:56 offset1:57
	s_waitcnt lgkmcnt(2)
	v_pk_add_f32 v[64:65], v[64:65], v[96:97] op_sel:[0,1] op_sel_hi:[1,0]
	ds_read2_b32 v[96:97], v104 offset0:24 offset1:25
	s_waitcnt lgkmcnt(2)
	v_pk_add_f32 v[48:49], v[48:49], v[98:99] op_sel:[0,1] op_sel_hi:[1,0]
	ds_read2_b32 v[98:99], v104 offset0:50 offset1:51
	s_waitcnt lgkmcnt(2)
	v_pk_add_f32 v[66:67], v[66:67], v[100:101] op_sel:[0,1] op_sel_hi:[1,0]
	ds_read2_b32 v[100:101], v104 offset0:18 offset1:19
	s_waitcnt lgkmcnt(1)
	v_pk_add_f32 v[68:69], v[68:69], v[98:99] op_sel:[0,1] op_sel_hi:[1,0]
	ds_read2_b32 v[98:99], v104 offset0:16 offset1:17
	s_waitcnt lgkmcnt(1)
	v_pk_add_f32 v[52:53], v[52:53], v[100:101] op_sel:[0,1] op_sel_hi:[1,0]
	ds_read2_b32 v[100:101], v104 offset0:42 offset1:43
	v_pk_add_f32 v[50:51], v[50:51], v[96:97] op_sel:[0,1] op_sel_hi:[1,0]
	ds_read2_b32 v[96:97], v104 offset0:48 offset1:49
	s_waitcnt lgkmcnt(1)
	v_pk_add_f32 v[72:73], v[72:73], v[100:101] op_sel:[0,1] op_sel_hi:[1,0]
	ds_read2_b32 v[100:101], v104 offset0:8 offset1:9
	s_waitcnt lgkmcnt(1)
	v_pk_add_f32 v[70:71], v[70:71], v[96:97] op_sel:[0,1] op_sel_hi:[1,0]
	ds_read2_b32 v[96:97], v104 offset0:10 offset1:11
	v_pk_add_f32 v[54:55], v[54:55], v[98:99] op_sel:[0,1] op_sel_hi:[1,0]
	ds_read2_b32 v[98:99], v104 offset0:40 offset1:41
	s_waitcnt lgkmcnt(2)
	v_pk_add_f32 v[58:59], v[58:59], v[100:101] op_sel:[0,1] op_sel_hi:[1,0]
	s_waitcnt lgkmcnt(1)
	v_pk_add_f32 v[56:57], v[56:57], v[96:97] op_sel:[0,1] op_sel_hi:[1,0]
	ds_read2_b32 v[96:97], v104 offset0:34 offset1:35
	s_waitcnt lgkmcnt(1)
	v_pk_add_f32 v[74:75], v[74:75], v[98:99] op_sel:[0,1] op_sel_hi:[1,0]
	ds_read2_b32 v[98:99], v104 offset0:2 offset1:3
	ds_read2_b32 v[102:103], v104 offset0:32 offset1:33
	ds_read2_b32 v[104:105], v104 offset1:1
	s_waitcnt lgkmcnt(3)
	v_pk_add_f32 v[76:77], v[76:77], v[96:97] op_sel:[0,1] op_sel_hi:[1,0]
	s_waitcnt lgkmcnt(2)
	v_pk_add_f32 v[60:61], v[60:61], v[98:99] op_sel:[0,1] op_sel_hi:[1,0]
	s_waitcnt lgkmcnt(1)
	v_pk_add_f32 v[78:79], v[78:79], v[102:103] op_sel:[0,1] op_sel_hi:[1,0]
	s_waitcnt lgkmcnt(0)
	v_pk_add_f32 v[62:63], v[62:63], v[104:105] op_sel:[0,1] op_sel_hi:[1,0]
	s_waitcnt lgkmcnt(0)
	v_mfma_f32_32x32x16_bf16 v[236:251], v[154:157], v[92:95], v[220:235]
	ds_read_b64_tr_b16 v[186:187], v218
	ds_read_b64_tr_b16 v[188:189], v218 offset:512
	ds_read_b64_tr_b16 v[190:191], v218 offset:1024
	ds_read_b64_tr_b16 v[192:193], v218 offset:1536
	ds_read_b64_tr_b16 v[194:195], v218 offset:2048
	ds_read_b64_tr_b16 v[196:197], v218 offset:2560
	ds_read_b64_tr_b16 v[198:199], v218 offset:3072
	ds_read_b64_tr_b16 v[200:201], v218 offset:3584
	ds_read_b64_tr_b16 v[202:203], v218 offset:4096
	ds_read_b64_tr_b16 v[204:205], v218 offset:4608
	ds_read_b64_tr_b16 v[206:207], v218 offset:5120
	v_mfma_f32_32x32x16_bf16 v[134:149], v[158:161], v[92:95], v[220:235]
	ds_read_b64_tr_b16 v[208:209], v218 offset:5632
	ds_read_b64_tr_b16 v[210:211], v218 offset:6144
	ds_read_b64_tr_b16 v[212:213], v218 offset:6656
	ds_read_b64_tr_b16 v[214:215], v218 offset:7168
	ds_read_b64_tr_b16 v[216:217], v218 offset:7680
	v_exp_f32_e32 v64, v64
	v_exp_f32_e32 v48, v48
	v_exp_f32_e32 v65, v65
	v_exp_f32_e32 v49, v49
	v_exp_f32_e32 v66, v66
	v_exp_f32_e32 v50, v50
	v_mfma_f32_32x32x16_bf16 v[236:251], v[162:165], v[88:91], v[236:251]
	v_exp_f32_e32 v67, v67
	v_exp_f32_e32 v51, v51
	v_add_f32_e32 v252, v48, v64
	v_exp_f32_e32 v68, v68
	v_exp_f32_e32 v52, v52
	v_add_f32_e32 v252, 0, v252
	v_add_f32_e32 v253, v49, v65
	v_exp_f32_e32 v69, v69
	v_exp_f32_e32 v53, v53
	v_add_f32_e32 v252, v253, v252
	v_add_f32_e32 v253, v50, v66
	v_mfma_f32_32x32x16_bf16 v[134:149], v[166:169], v[88:91], v[134:149]
	v_exp_f32_e32 v70, v70
	v_exp_f32_e32 v54, v54
	v_add_f32_e32 v252, v253, v252
	v_add_f32_e32 v253, v51, v67
	v_exp_f32_e32 v71, v71
	v_exp_f32_e32 v55, v55
	v_add_f32_e32 v252, v253, v252
	v_add_f32_e32 v253, v52, v68
	v_exp_f32_e32 v72, v72
	v_exp_f32_e32 v56, v56
	v_add_f32_e32 v252, v253, v252
	v_mfma_f32_32x32x16_bf16 v[236:251], v[170:173], v[84:87], v[236:251]
	v_add_f32_e32 v253, v53, v69
	v_exp_f32_e32 v73, v73
	v_exp_f32_e32 v57, v57
	v_add_f32_e32 v252, v253, v252
	v_add_f32_e32 v253, v54, v70
	v_exp_f32_e32 v74, v74
	v_exp_f32_e32 v58, v58
	v_add_f32_e32 v252, v253, v252
	v_add_f32_e32 v253, v55, v71
	v_exp_f32_e32 v75, v75
	v_exp_f32_e32 v59, v59
	v_mfma_f32_32x32x16_bf16 v[134:149], v[174:177], v[84:87], v[134:149]
	v_add_f32_e32 v252, v253, v252
	v_add_f32_e32 v253, v56, v72
	v_exp_f32_e32 v76, v76
	v_exp_f32_e32 v60, v60
	v_add_f32_e32 v252, v253, v252
	v_add_f32_e32 v253, v57, v73
	v_exp_f32_e32 v77, v77
	v_exp_f32_e32 v61, v61
	v_add_f32_e32 v252, v253, v252
	v_add_f32_e32 v253, v58, v74
	v_exp_f32_e32 v78, v78
	v_mfma_f32_32x32x16_bf16 v[236:251], v[178:181], v[80:83], v[236:251]
	v_exp_f32_e32 v62, v62
	v_add_f32_e32 v252, v253, v252
	v_add_f32_e32 v253, v59, v75
	v_exp_f32_e32 v79, v79
	v_exp_f32_e32 v63, v63
	v_add_f32_e32 v252, v253, v252
	v_add_f32_e32 v253, v60, v76
	v_add_f32_e32 v252, v253, v252
	v_add_f32_e32 v253, v61, v77
	v_add_f32_e32 v252, v253, v252
	v_add_f32_e32 v253, v62, v78
	v_mfma_f32_32x32x16_bf16 v[134:149], v[182:185], v[80:83], v[134:149]
	v_add_f32_e32 v252, v253, v252
	v_add_f32_e32 v253, v63, v79
	v_add_f32_e32 v252, v253, v252
	v_add_f32_e32 v131, v131, v252
	v_cvt_pk_bf16_f32 v108, v64, v65
	v_cvt_pk_bf16_f32 v109, v66, v67
	v_cvt_pk_bf16_f32 v110, v68, v69
	v_cvt_pk_bf16_f32 v111, v70, v71
	v_cvt_pk_bf16_f32 v104, v72, v73
	v_cvt_pk_bf16_f32 v105, v74, v75
	v_cvt_pk_bf16_f32 v106, v76, v77
	v_cvt_pk_bf16_f32 v107, v78, v79
	v_cvt_pk_bf16_f32 v100, v48, v49
	v_cvt_pk_bf16_f32 v101, v50, v51
	v_cvt_pk_bf16_f32 v102, v52, v53
	v_cvt_pk_bf16_f32 v103, v54, v55
	v_cvt_pk_bf16_f32 v96, v56, v57
	v_cvt_pk_bf16_f32 v97, v58, v59
	v_cvt_pk_bf16_f32 v98, v60, v61
	v_cvt_pk_bf16_f32 v99, v62, v63
	s_branch .Lmb1_A_tail
.Lmb1_A_wo:
	s_cmp_eq_u32 s43, 1
	s_cbranch_scc1 .Lmb1_A_w1
	s_waitcnt vmcnt(0) lgkmcnt(0)
	s_branch .Lmb1_A_wd
.Lmb1_A_w1:
	s_waitcnt vmcnt(1) lgkmcnt(0)
	s_branch .Lmb1_A_wd
.Lmb1_B_near:
	s_waitcnt lgkmcnt(8)
	v_mfma_f32_32x32x16_bf16 v[16:31], v[108:111], v[186:189], v[16:31]
	v_mfma_f32_32x32x16_bf16 v[16:31], v[104:107], v[190:193], v[16:31]
	v_mfma_f32_32x32x16_bf16 v[16:31], v[100:103], v[194:197], v[16:31]
	v_mfma_f32_32x32x16_bf16 v[16:31], v[96:99], v[198:201], v[16:31]
	v_mfma_f32_32x32x16_bf16 v[32:47], v[108:111], v[202:205], v[32:47]
	v_mfma_f32_32x32x16_bf16 v[32:47], v[104:107], v[206:209], v[32:47]
	v_mfma_f32_32x32x16_bf16 v[32:47], v[100:103], v[210:213], v[32:47]
	v_mfma_f32_32x32x16_bf16 v[32:47], v[96:99], v[214:217], v[32:47]
	s_lshr_b32 s44, s34, 2
	s_cmp_eq_u32 s44, s91
	s_cselect_b64 s[8:9], -1, 0
	s_lshl_b32 s44, 1, s44
	v_and_b32_e32 v96, s44, v129
	v_cmp_ne_u32_e32 vcc, 0, v96
	s_or_b64 vcc, s[8:9], vcc
	s_nop 0
	v_cndmask_b32_e32 v96, v127, v112, vcc
	v_lshl_add_u32 v96, v96, 2, 0
	v_add_u32_e32 v104, 0x1d000, v96
	ds_read2_b32 v[96:97], v104 offset0:58 offset1:59
	ds_read2_b32 v[98:99], v104 offset0:26 offset1:27
	ds_read2_b32 v[100:101], v104 offset0:56 offset1:57
	s_waitcnt lgkmcnt(2)
	v_pk_add_f32 v[236:237], v[236:237], v[96:97] op_sel:[0,1] op_sel_hi:[1,0]
	ds_read2_b32 v[96:97], v104 offset0:24 offset1:25
	s_waitcnt lgkmcnt(2)
	v_pk_add_f32 v[134:135], v[134:135], v[98:99] op_sel:[0,1] op_sel_hi:[1,0]
	ds_read2_b32 v[98:99], v104 offset0:50 offset1:51
	s_waitcnt lgkmcnt(2)
	v_pk_add_f32 v[238:239], v[238:239], v[100:101] op_sel:[0,1] op_sel_hi:[1,0]
	ds_read2_b32 v[100:101], v104 offset0:18 offset1:19
	s_waitcnt lgkmcnt(1)
	v_pk_add_f32 v[240:241], v[240:241], v[98:99] op_sel:[0,1] op_sel_hi:[1,0]
	ds_read2_b32 v[98:99], v104 offset0:16 offset1:17
	s_waitcnt lgkmcnt(1)
	v_pk_add_f32 v[138:139], v[138:139], v[100:101] op_sel:[0,1] op_sel_hi:[1,0]
	ds_read2_b32 v[100:101], v104 offset0:42 offset1:43
	v_pk_add_f32 v[136:137], v[136:137], v[96:97] op_sel:[0,1] op_sel_hi:[1,0]
	ds_read2_b32 v[96:97], v104 offset0:48 offset1:49
	s_waitcnt lgkmcnt(1)
	v_pk_add_f32 v[244:245], v[244:245], v[100:101] op_sel:[0,1] op_sel_hi:[1,0]
	ds_read2_b32 v[100:101], v104 offset0:8 offset1:9
	s_waitcnt lgkmcnt(1)
	v_pk_add_f32 v[242:243], v[242:243], v[96:97] op_sel:[0,1] op_sel_hi:[1,0]
	ds_read2_b32 v[96:97], v104 offset0:10 offset1:11
	v_pk_add_f32 v[140:141], v[140:141], v[98:99] op_sel:[0,1] op_sel_hi:[1,0]
	ds_read2_b32 v[98:99], v104 offset0:40 offset1:41
	s_waitcnt lgkmcnt(2)
	v_pk_add_f32 v[144:145], v[144:145], v[100:101] op_sel:[0,1] op_sel_hi:[1,0]
	s_waitcnt lgkmcnt(1)
	v_pk_add_f32 v[142:143], v[142:143], v[96:97] op_sel:[0,1] op_sel_hi:[1,0]
	ds_read2_b32 v[96:97], v104 offset0:34 offset1:35
	s_waitcnt lgkmcnt(1)
	v_pk_add_f32 v[246:247], v[246:247], v[98:99] op_sel:[0,1] op_sel_hi:[1,0]
	ds_read2_b32 v[98:99], v104 offset0:2 offset1:3
	ds_read2_b32 v[102:103], v104 offset0:32 offset1:33
	ds_read2_b32 v[104:105], v104 offset1:1
	s_waitcnt lgkmcnt(3)
	v_pk_add_f32 v[248:249], v[248:249], v[96:97] op_sel:[0,1] op_sel_hi:[1,0]
	s_waitcnt lgkmcnt(2)
	v_pk_add_f32 v[146:147], v[146:147], v[98:99] op_sel:[0,1] op_sel_hi:[1,0]
	s_waitcnt lgkmcnt(1)
	v_pk_add_f32 v[250:251], v[250:251], v[102:103] op_sel:[0,1] op_sel_hi:[1,0]
	s_waitcnt lgkmcnt(0)
	v_pk_add_f32 v[148:149], v[148:149], v[104:105] op_sel:[0,1] op_sel_hi:[1,0]
	s_waitcnt lgkmcnt(0)
	v_mfma_f32_32x32x16_bf16 v[64:79], v[154:157], v[92:95], v[220:235]
	ds_read_b64_tr_b16 v[186:187], v218
	ds_read_b64_tr_b16 v[188:189], v218 offset:512
	ds_read_b64_tr_b16 v[190:191], v218 offset:1024
	ds_read_b64_tr_b16 v[192:193], v218 offset:1536
	ds_read_b64_tr_b16 v[194:195], v218 offset:2048
	ds_read_b64_tr_b16 v[196:197], v218 offset:2560
	ds_read_b64_tr_b16 v[198:199], v218 offset:3072
	ds_read_b64_tr_b16 v[200:201], v218 offset:3584
	ds_read_b64_tr_b16 v[202:203], v218 offset:4096
	ds_read_b64_tr_b16 v[204:205], v218 offset:4608
	ds_read_b64_tr_b16 v[206:207], v218 offset:5120
	v_mfma_f32_32x32x16_bf16 v[48:63], v[158:161], v[92:95], v[220:235]
	ds_read_b64_tr_b16 v[208:209], v218 offset:5632
	ds_read_b64_tr_b16 v[210:211], v218 offset:6144
	ds_read_b64_tr_b16 v[212:213], v218 offset:6656
	ds_read_b64_tr_b16 v[214:215], v218 offset:7168
	ds_read_b64_tr_b16 v[216:217], v218 offset:7680
	v_exp_f32_e32 v236, v236
	v_exp_f32_e32 v134, v134
	v_exp_f32_e32 v237, v237
	v_exp_f32_e32 v135, v135
	v_exp_f32_e32 v238, v238
	v_exp_f32_e32 v136, v136
	v_mfma_f32_32x32x16_bf16 v[64:79], v[162:165], v[88:91], v[64:79]
	v_exp_f32_e32 v239, v239
	v_exp_f32_e32 v137, v137
	v_add_f32_e32 v252, v134, v236
	v_exp_f32_e32 v240, v240
	v_exp_f32_e32 v138, v138
	v_add_f32_e32 v252, 0, v252
	v_add_f32_e32 v253, v135, v237
	v_exp_f32_e32 v241, v241
	v_exp_f32_e32 v139, v139
	v_add_f32_e32 v252, v253, v252
	v_add_f32_e32 v253, v136, v238
	v_mfma_f32_32x32x16_bf16 v[48:63], v[166:169], v[88:91], v[48:63]
	v_exp_f32_e32 v242, v242
	v_exp_f32_e32 v140, v140
	v_add_f32_e32 v252, v253, v252
	v_add_f32_e32 v253, v137, v239
	v_exp_f32_e32 v243, v243
	v_exp_f32_e32 v141, v141
	v_add_f32_e32 v252, v253, v252
	v_add_f32_e32 v253, v138, v240
	v_exp_f32_e32 v244, v244
	v_exp_f32_e32 v142, v142
	v_add_f32_e32 v252, v253, v252
	v_mfma_f32_32x32x16_bf16 v[64:79], v[170:173], v[84:87], v[64:79]
	v_add_f32_e32 v253, v139, v241
	v_exp_f32_e32 v245, v245
	v_exp_f32_e32 v143, v143
	v_add_f32_e32 v252, v253, v252
	v_add_f32_e32 v253, v140, v242
	v_exp_f32_e32 v246, v246
	v_exp_f32_e32 v144, v144
	v_add_f32_e32 v252, v253, v252
	v_add_f32_e32 v253, v141, v243
	v_exp_f32_e32 v247, v247
	v_exp_f32_e32 v145, v145
	v_mfma_f32_32x32x16_bf16 v[48:63], v[174:177], v[84:87], v[48:63]
	v_add_f32_e32 v252, v253, v252
	v_add_f32_e32 v253, v142, v244
	v_exp_f32_e32 v248, v248
	v_exp_f32_e32 v146, v146
	v_add_f32_e32 v252, v253, v252
	v_add_f32_e32 v253, v143, v245
	v_exp_f32_e32 v249, v249
	v_exp_f32_e32 v147, v147
	v_add_f32_e32 v252, v253, v252
	v_add_f32_e32 v253, v144, v246
	v_exp_f32_e32 v250, v250
	v_mfma_f32_32x32x16_bf16 v[64:79], v[178:181], v[80:83], v[64:79]
	v_exp_f32_e32 v148, v148
	v_add_f32_e32 v252, v253, v252
	v_add_f32_e32 v253, v145, v247
	v_exp_f32_e32 v251, v251
	v_exp_f32_e32 v149, v149
	v_add_f32_e32 v252, v253, v252
	v_add_f32_e32 v253, v146, v248
	v_add_f32_e32 v252, v253, v252
	v_add_f32_e32 v253, v147, v249
	v_add_f32_e32 v252, v253, v252
	v_add_f32_e32 v253, v148, v250
	v_mfma_f32_32x32x16_bf16 v[48:63], v[182:185], v[80:83], v[48:63]
	v_add_f32_e32 v252, v253, v252
	v_add_f32_e32 v253, v149, v251
	v_add_f32_e32 v252, v253, v252
	v_add_f32_e32 v131, v131, v252
	v_cvt_pk_bf16_f32 v108, v236, v237
	v_cvt_pk_bf16_f32 v109, v238, v239
	v_cvt_pk_bf16_f32 v110, v240, v241
	v_cvt_pk_bf16_f32 v111, v242, v243
	v_cvt_pk_bf16_f32 v104, v244, v245
	v_cvt_pk_bf16_f32 v105, v246, v247
	v_cvt_pk_bf16_f32 v106, v248, v249
	v_cvt_pk_bf16_f32 v107, v250, v251
	v_cvt_pk_bf16_f32 v100, v134, v135
	v_cvt_pk_bf16_f32 v101, v136, v137
	v_cvt_pk_bf16_f32 v102, v138, v139
	v_cvt_pk_bf16_f32 v103, v140, v141
	v_cvt_pk_bf16_f32 v96, v142, v143
	v_cvt_pk_bf16_f32 v97, v144, v145
	v_cvt_pk_bf16_f32 v98, v146, v147
	v_cvt_pk_bf16_f32 v99, v148, v149
	s_branch .Lmb1_B_tail

; template <int MODE> __device__ __forceinline__ void attn_unit(int b, int h, int qb, int t_lo, const bf16_t* Q, const bf16_t* __restrict__ K, const bf16_t* __restrict__ V, bf16_t* O, ATT_LAS unsigned char* lds, const int wid, const float kn2, const float bmax) {
;     ...
;     ATT_ITER(n - 1, false, true);
;     ...
;     if (grp == 0) asm volatile("s_barrier" ::: "memory");
.Lmb1_exitfix:
	s_and_b64 vcc, exec, s[6:7]
	s_cbranch_vccnz .LBB0_1075
	s_barrier
	s_branch .LBB0_1075

; template <int MODE> __device__ __forceinline__ void attn_unit(int b, int h, int qb, int t_lo, const bf16_t* Q, const bf16_t* __restrict__ K, const bf16_t* __restrict__ V, bf16_t* O, ATT_LAS unsigned char* lds, const int wid, const float kn2, const float bmax) {
;     ...
;     float l_reg = 0.f; f32x16 o[2]; o[0] = f32x16{}; o[1] = f32x16{};
;     f32x16 negm;
; #pragma unroll
;     for (int r = 0; r < 16; ++r) negm[r] = -ref;
;     asm volatile("" : "+v"(negm));
;     const float NEG = -INFINITY;
;     f32x16 p0, p1; u32x4 pw0 = {}, pw1 = {}, pw2 = {}, pw3 = {};
;     const int grp = ATT_LOCKSTEP ? 2 : (wid >> 2);
;     asm volatile("s_waitcnt vmcnt(0) lgkmcnt(0)\n\ts_barrier" ::: "memory");
;     if (grp == 1) asm volatile("s_barrier" ::: "memory");
.LBB0_2382:
	s_nop 8
	v_exp_f32_e32 v56, v32
	s_nop 0
	v_exp_f32_e32 v57, v16
	v_exp_f32_e32 v112, v33
	v_exp_f32_e32 v16, v17
	v_exp_f32_e32 v58, v18
	v_add_f32_e32 v17, v57, v56
	v_exp_f32_e32 v18, v19
	v_pk_add_f32 v[32:33], v[16:17], v[112:113]
	v_exp_f32_e32 v17, v34
	v_pk_add_f32 v[32:33], v[32:33], v[32:33] op_sel_hi:[0,1]
	v_exp_f32_e32 v32, v35
	v_lshlrev_b32_e32 v59, 1, v52
	v_add_f32_e32 v19, v58, v17
	s_mov_b64 s[10:11], 0x80000
	v_pk_add_f32 v[34:35], v[18:19], v[32:33]
	v_exp_f32_e32 v19, v36
	v_pk_add_f32 v[34:35], v[34:35], v[34:35] op_sel_hi:[0,1]
	v_exp_f32_e32 v33, v20
	v_exp_f32_e32 v34, v37
	v_exp_f32_e32 v20, v21
	v_lshl_add_u64 v[114:115], v[48:49], 0, s[10:11]
	v_add_f32_e32 v21, v33, v19
	s_add_i32 s10, s86, s42
	v_pk_add_f32 v[36:37], v[20:21], v[34:35]
	v_exp_f32_e32 v21, v38
	v_pk_add_f32 v[36:37], v[36:37], v[36:37] op_sel_hi:[0,1]
	v_exp_f32_e32 v35, v22
	v_exp_f32_e32 v36, v39
	v_exp_f32_e32 v22, v23
	v_cvt_pk_bf16_f32 v100, v57, v16
	v_add_f32_e32 v23, v35, v21
	s_waitcnt vmcnt(0) lgkmcnt(0)
	s_barrier
	v_pk_add_f32 v[38:39], v[22:23], v[36:37]
	v_exp_f32_e32 v23, v40
	v_pk_add_f32 v[38:39], v[38:39], v[38:39] op_sel_hi:[0,1]
	v_exp_f32_e32 v37, v24
	v_exp_f32_e32 v38, v41
	v_exp_f32_e32 v24, v25
	v_and_b32_e32 v25, 32, v59
	v_add_u32_e32 v59, s89, v25
	v_add_f32_e32 v25, v37, v23
	v_pk_add_f32 v[40:41], v[24:25], v[38:39]
	v_exp_f32_e32 v25, v42
	v_pk_add_f32 v[40:41], v[40:41], v[40:41] op_sel_hi:[0,1]
	v_exp_f32_e32 v39, v26
	v_exp_f32_e32 v40, v43
	v_exp_f32_e32 v26, v27
	v_lshrrev_b32_e32 v27, 2, v52
	v_and_or_b32 v52, v27, 3, v55
	v_add_f32_e32 v27, v39, v25
	v_pk_add_f32 v[42:43], v[26:27], v[40:41]
	v_exp_f32_e32 v27, v44
	v_pk_add_f32 v[42:43], v[42:43], v[42:43] op_sel_hi:[0,1]
	v_exp_f32_e32 v41, v28
	v_exp_f32_e32 v42, v45
	v_exp_f32_e32 v28, v29
	v_add_u32_e32 v16, s10, v54
	v_add_f32_e32 v29, v41, v27
	s_lshl_b32 s28, s93, 2
	v_pk_add_f32 v[44:45], v[28:29], v[42:43]
	v_exp_f32_e32 v29, v46
	v_pk_add_f32 v[44:45], v[44:45], v[44:45] op_sel_hi:[0,1]
	v_exp_f32_e32 v43, v30
	v_exp_f32_e32 v44, v47
	v_exp_f32_e32 v30, v31
	v_lshlrev_b32_e32 v52, 6, v52
	v_add_f32_e32 v31, v43, v29
	v_cvt_pk_bf16_f32 v108, v56, v112
	v_pk_add_f32 v[46:47], v[30:31], v[44:45]
	v_sub_u32_e32 v112, v16, v55
	v_add_f32_e32 v31, v46, v47
	v_mov_b32_e32 v16, 0
	s_add_i32 s29, s28, -2
	s_mov_b32 s30, 1
	s_add_i32 s31, s28, 4
	v_add3_u32 v132, v59, v53, v52
	s_mov_b32 s43, 0
	v_add_f32_e32 v131, 0, v31
	v_cvt_pk_bf16_f32 v109, v17, v32
	v_cvt_pk_bf16_f32 v110, v19, v34
	v_cvt_pk_bf16_f32 v111, v21, v36
	v_cvt_pk_bf16_f32 v104, v23, v38
	v_cvt_pk_bf16_f32 v105, v25, v40
	v_cvt_pk_bf16_f32 v106, v27, v42
	v_cvt_pk_bf16_f32 v107, v29, v44
	v_cvt_pk_bf16_f32 v101, v58, v18
	v_cvt_pk_bf16_f32 v102, v33, v20
	v_cvt_pk_bf16_f32 v103, v35, v22
	v_cvt_pk_bf16_f32 v96, v37, v24
	v_cvt_pk_bf16_f32 v97, v39, v26
	v_cvt_pk_bf16_f32 v98, v41, v28
	v_cvt_pk_bf16_f32 v99, v43, v30
	s_or_b32 s34, s28, 2
	v_lshl_add_u64 v[116:117], v[50:51], 0, s[24:25]
	v_mov_b32_e32 v17, v16
	v_mov_b32_e32 v18, v16
	v_mov_b32_e32 v19, v16
	v_mov_b32_e32 v20, v16
	v_mov_b32_e32 v21, v16
	v_mov_b32_e32 v22, v16
	v_mov_b32_e32 v23, v16
	v_mov_b32_e32 v24, v16
	v_mov_b32_e32 v25, v16
	v_mov_b32_e32 v26, v16
	v_mov_b32_e32 v27, v16
	v_mov_b32_e32 v28, v16
	v_mov_b32_e32 v29, v16
	v_mov_b32_e32 v30, v16
	v_mov_b32_e32 v31, v16
	v_mov_b32_e32 v32, v16
	v_mov_b32_e32 v33, v16
	v_mov_b32_e32 v34, v16
	v_mov_b32_e32 v35, v16
	v_mov_b32_e32 v36, v16
	v_mov_b32_e32 v37, v16
	v_mov_b32_e32 v38, v16
	v_mov_b32_e32 v39, v16
	v_mov_b32_e32 v40, v16
	v_mov_b32_e32 v41, v16
	v_mov_b32_e32 v42, v16
	v_mov_b32_e32 v43, v16
	v_mov_b32_e32 v44, v16
	v_mov_b32_e32 v45, v16
	v_mov_b32_e32 v46, v16
	v_mov_b32_e32 v47, v16
	s_and_b64 vcc, exec, s[6:7]
	s_cbranch_vccz .Lmb3_al
	s_barrier
.Lmb3_al:
	s_add_i32 s35, s30, -1
	s_mov_b32 s37, 0
	s_cmp_ge_u32 s35, s28
	s_cbranch_scc1 .Lmb3_pK
	s_and_b32 s42, s43, 0x6000
	s_add_i32 s42, s42, s74
	s_mov_b32 s99, m0
	s_mov_b32 m0, s42
	s_nop 0
	global_load_lds_dwordx4 v[114:115], off
	s_mov_b32 m0, s99
.Lmb3_pK:
	s_add_i32 s42, s35, 3
	s_cmp_ge_u32 s42, s31
	s_cbranch_scc1 .Lmb3_pV
	s_add_i32 s42, s43, 0x6000
	s_and_b32 s42, s42, 0x6000
	s_add_i32 s42, s42, s75
	s_mov_b32 s99, m0
	s_mov_b32 m0, s42
	s_nop 0
	global_load_lds_dwordx4 v[116:117], off
	s_mov_b32 m0, s99
.Lmb3_pV:
	v_lshl_add_u64 v[114:115], v[114:115], 0, s[20:21]
	v_lshl_add_u64 v[116:117], v[116:117], 0, s[20:21]
	s_add_i32 s36, s43, 0x2000
	s_and_b32 s42, s36, 0x6000
	v_add_u32_e32 v133, s42, v130
	ds_read_b128 v[154:157], v133
	ds_read_b128 v[158:161], v133 offset:512
	ds_read_b128 v[162:165], v133 offset:2048
	ds_read_b128 v[166:169], v133 offset:2560
	ds_read_b128 v[170:173], v133 offset:4096
	ds_read_b128 v[174:177], v133 offset:4608
	ds_read_b128 v[178:181], v133 offset:6144
	ds_read_b128 v[182:185], v133 offset:6656
	s_and_b32 s42, s43, 0x6000
	v_add_u32_e32 v218, s42, v132
	ds_read_b64_tr_b16 v[186:187], v218
	ds_read_b64_tr_b16 v[188:189], v218 offset:512
	ds_read_b64_tr_b16 v[190:191], v218 offset:1024
	ds_read_b64_tr_b16 v[192:193], v218 offset:1536
	ds_read_b64_tr_b16 v[194:195], v218 offset:2048
	ds_read_b64_tr_b16 v[196:197], v218 offset:2560
	ds_read_b64_tr_b16 v[198:199], v218 offset:3072
	ds_read_b64_tr_b16 v[200:201], v218 offset:3584
	ds_read_b64_tr_b16 v[202:203], v218 offset:4096
	ds_read_b64_tr_b16 v[204:205], v218 offset:4608
	ds_read_b64_tr_b16 v[206:207], v218 offset:5120
	ds_read_b64_tr_b16 v[208:209], v218 offset:5632
	ds_read_b64_tr_b16 v[210:211], v218 offset:6144
	ds_read_b64_tr_b16 v[212:213], v218 offset:6656
	ds_read_b64_tr_b16 v[214:215], v218 offset:7168
	ds_read_b64_tr_b16 v[216:217], v218 offset:7680
	s_lshr_b32 s42, s30, 2
	v_lshrrev_b32_e32 v219, s42, v129
	v_and_b32_e32 v219, 1, v219
	v_cmp_eq_u32_e32 vcc, 1, v219
	s_cmp_ge_i32 s30, s29
	s_nop 0
	v_cndmask_b32_e32 v219, v126, v128, vcc
	s_cselect_b64 vcc, 0, -1
	s_nop 1
	v_cndmask_b32_e32 v219, 0, v219, vcc
	v_add_f32_e32 v220, v0, v219
	v_add_f32_e32 v221, v1, v219
	v_add_f32_e32 v222, v2, v219
	v_add_f32_e32 v223, v3, v219
	v_add_f32_e32 v224, v4, v219
	v_add_f32_e32 v225, v5, v219
	v_add_f32_e32 v226, v6, v219
	v_add_f32_e32 v227, v7, v219
	v_add_f32_e32 v228, v8, v219
	v_add_f32_e32 v229, v9, v219
	v_add_f32_e32 v230, v10, v219
	v_add_f32_e32 v231, v11, v219
	v_add_f32_e32 v232, v12, v219
	v_add_f32_e32 v233, v13, v219
	v_add_f32_e32 v234, v14, v219
	v_add_f32_e32 v235, v15, v219
	s_add_i32 s98, s30, 1
	s_waitcnt lgkmcnt(15)
	v_mfma_f32_32x32x16_bf16 v[64:79], v[154:157], v[92:95], v[220:235]
	v_mfma_f32_32x32x16_bf16 v[48:63], v[158:161], v[92:95], v[220:235]
	s_waitcnt lgkmcnt(15)
	v_mfma_f32_32x32x16_bf16 v[64:79], v[162:165], v[88:91], v[64:79]
	v_mfma_f32_32x32x16_bf16 v[48:63], v[166:169], v[88:91], v[48:63]
	s_waitcnt lgkmcnt(15)
	v_mfma_f32_32x32x16_bf16 v[64:79], v[170:173], v[84:87], v[64:79]
	v_mfma_f32_32x32x16_bf16 v[48:63], v[174:177], v[84:87], v[48:63]
	s_waitcnt lgkmcnt(15)
	v_mfma_f32_32x32x16_bf16 v[64:79], v[178:181], v[80:83], v[64:79]
	v_mfma_f32_32x32x16_bf16 v[48:63], v[182:185], v[80:83], v[48:63]
	s_lshr_b32 s42, s98, 2
	v_lshrrev_b32_e32 v219, s42, v129
	v_and_b32_e32 v219, 1, v219
	v_cmp_eq_u32_e32 vcc, 1, v219
	s_cmp_ge_i32 s98, s29
	s_nop 0
	v_cndmask_b32_e32 v219, v126, v128, vcc
	s_cselect_b64 vcc, 0, -1
	s_nop 1
	v_cndmask_b32_e32 v219, 0, v219, vcc
	v_add_f32_e32 v220, v0, v219
	v_add_f32_e32 v221, v1, v219
	v_add_f32_e32 v222, v2, v219
	v_add_f32_e32 v223, v3, v219
	v_add_f32_e32 v224, v4, v219
	v_add_f32_e32 v225, v5, v219
	v_add_f32_e32 v226, v6, v219
	v_add_f32_e32 v227, v7, v219
	v_add_f32_e32 v228, v8, v219
	v_add_f32_e32 v229, v9, v219
	v_add_f32_e32 v230, v10, v219
	v_add_f32_e32 v231, v11, v219
	v_add_f32_e32 v232, v12, v219
	v_add_f32_e32 v233, v13, v219
	v_add_f32_e32 v234, v14, v219
	v_add_f32_e32 v235, v15, v219
	s_waitcnt lgkmcnt(0)
.LBB0_2383:
.LBB0_2384:
.LBB0_2386:
.Lmb3_A:
	s_barrier
	s_add_i32 s42, s35, 1
	s_cmp_ge_u32 s42, s28
	s_cbranch_scc1 .Lmb3_skKA
	s_add_i32 s42, s43, 0x2000
	s_and_b32 s42, s42, 0x6000
	s_add_i32 s42, s42, s74
	s_mov_b32 s99, m0
	s_mov_b32 m0, s42
	s_nop 0
	global_load_lds_dwordx4 v[114:115], off
	s_mov_b32 m0, s99
	s_mov_b32 s37, 1
.Lmb3_skKA:
	s_add_i32 s42, s35, 4
	s_cmp_ge_u32 s42, s31
	s_cbranch_scc1 .Lmb3_skVA
	s_and_b32 s42, s43, 0x6000
	s_add_i32 s42, s42, s75
	s_mov_b32 s99, m0
	s_mov_b32 m0, s42
	s_nop 0
	global_load_lds_dwordx4 v[116:117], off
	s_mov_b32 m0, s99
	s_add_i32 s37, s37, 1
.Lmb3_skVA:
	s_add_i32 s36, s43, 0x2000
	s_add_i32 s98, s43, 0x4000
	s_and_b32 s42, s98, 0x6000
	v_add_u32_e32 v133, s42, v130
	ds_read_b128 v[154:157], v133
	ds_read_b128 v[158:161], v133 offset:512
	ds_read_b128 v[162:165], v133 offset:2048
	ds_read_b128 v[166:169], v133 offset:2560
	ds_read_b128 v[170:173], v133 offset:4096
	ds_read_b128 v[174:177], v133 offset:4608
	ds_read_b128 v[178:181], v133 offset:6144
	ds_read_b128 v[182:185], v133 offset:6656
	s_and_b32 s42, s36, 0x6000
	v_add_u32_e32 v218, s42, v132
	s_add_i32 s98, s30, 2
	s_cmp_ge_i32 s30, s29
	s_cbranch_scc1 .Lmb3_A_near
	v_mfma_f32_32x32x16_bf16 v[16:31], v[108:111], v[186:189], v[16:31]
	v_exp_f32_e32 v64, v64
	v_exp_f32_e32 v48, v48
	v_mfma_f32_32x32x16_bf16 v[16:31], v[104:107], v[190:193], v[16:31]
	v_exp_f32_e32 v65, v65
	v_exp_f32_e32 v49, v49
	v_add_f32_e32 v252, v64, v48
	v_mfma_f32_32x32x16_bf16 v[16:31], v[100:103], v[194:197], v[16:31]
	v_exp_f32_e32 v66, v66
	v_exp_f32_e32 v50, v50
	v_add_f32_e32 v253, v65, v49
	v_add_f32_e32 v252, v252, v253
	v_mfma_f32_32x32x16_bf16 v[16:31], v[96:99], v[198:201], v[16:31]
	v_exp_f32_e32 v67, v67
	v_exp_f32_e32 v51, v51
	v_add_f32_e32 v253, v66, v50
	v_add_f32_e32 v252, v252, v253
	v_mfma_f32_32x32x16_bf16 v[32:47], v[108:111], v[202:205], v[32:47]
	v_exp_f32_e32 v68, v68
	v_exp_f32_e32 v52, v52
	v_add_f32_e32 v253, v67, v51
	v_add_f32_e32 v252, v252, v253
	ds_read_b64_tr_b16 v[186:187], v218
	ds_read_b64_tr_b16 v[188:189], v218 offset:512
	v_mfma_f32_32x32x16_bf16 v[32:47], v[104:107], v[206:209], v[32:47]
	v_exp_f32_e32 v69, v69
	v_exp_f32_e32 v53, v53
	v_add_f32_e32 v253, v68, v52
	v_add_f32_e32 v252, v252, v253
	ds_read_b64_tr_b16 v[190:191], v218 offset:1024
	ds_read_b64_tr_b16 v[192:193], v218 offset:1536
	v_mfma_f32_32x32x16_bf16 v[32:47], v[100:103], v[210:213], v[32:47]
	v_exp_f32_e32 v70, v70
	v_exp_f32_e32 v54, v54
	v_add_f32_e32 v253, v69, v53
	v_add_f32_e32 v252, v252, v253
	ds_read_b64_tr_b16 v[194:195], v218 offset:2048
	ds_read_b64_tr_b16 v[196:197], v218 offset:2560
	v_mfma_f32_32x32x16_bf16 v[32:47], v[96:99], v[214:217], v[32:47]
	v_exp_f32_e32 v71, v71
	v_exp_f32_e32 v55, v55
	v_add_f32_e32 v253, v70, v54
	v_add_f32_e32 v252, v252, v253
	ds_read_b64_tr_b16 v[198:199], v218 offset:3072
	ds_read_b64_tr_b16 v[200:201], v218 offset:3584
	s_waitcnt lgkmcnt(8)
	v_mfma_f32_32x32x16_bf16 v[236:251], v[154:157], v[92:95], v[220:235]
	v_exp_f32_e32 v72, v72
	v_exp_f32_e32 v56, v56
	v_add_f32_e32 v253, v71, v55
	v_add_f32_e32 v252, v252, v253
	v_cvt_pk_bf16_f32 v108, v64, v65
	v_cvt_pk_bf16_f32 v100, v48, v49
	ds_read_b64_tr_b16 v[202:203], v218 offset:4096
	ds_read_b64_tr_b16 v[204:205], v218 offset:4608
	v_mfma_f32_32x32x16_bf16 v[134:149], v[158:161], v[92:95], v[220:235]
	v_exp_f32_e32 v73, v73
	v_exp_f32_e32 v57, v57
	v_add_f32_e32 v253, v72, v56
	v_add_f32_e32 v252, v252, v253
	v_cvt_pk_bf16_f32 v109, v66, v67
	v_cvt_pk_bf16_f32 v101, v50, v51
	ds_read_b64_tr_b16 v[206:207], v218 offset:5120
	ds_read_b64_tr_b16 v[208:209], v218 offset:5632
	v_mfma_f32_32x32x16_bf16 v[236:251], v[162:165], v[88:91], v[236:251]
	v_exp_f32_e32 v74, v74
	v_exp_f32_e32 v58, v58
	v_add_f32_e32 v253, v73, v57
	v_add_f32_e32 v252, v252, v253
	v_cvt_pk_bf16_f32 v110, v68, v69
	v_cvt_pk_bf16_f32 v102, v52, v53
	ds_read_b64_tr_b16 v[210:211], v218 offset:6144
	ds_read_b64_tr_b16 v[212:213], v218 offset:6656
	v_mfma_f32_32x32x16_bf16 v[134:149], v[166:169], v[88:91], v[134:149]
	v_exp_f32_e32 v75, v75
	v_exp_f32_e32 v59, v59
	v_add_f32_e32 v253, v74, v58
	v_add_f32_e32 v252, v252, v253
	v_cvt_pk_bf16_f32 v111, v70, v71
	v_cvt_pk_bf16_f32 v103, v54, v55
	ds_read_b64_tr_b16 v[214:215], v218 offset:7168
	ds_read_b64_tr_b16 v[216:217], v218 offset:7680
	v_mfma_f32_32x32x16_bf16 v[236:251], v[170:173], v[84:87], v[236:251]
	v_exp_f32_e32 v76, v76
	v_exp_f32_e32 v60, v60
	v_add_f32_e32 v253, v75, v59
	v_add_f32_e32 v252, v252, v253
	v_cvt_pk_bf16_f32 v104, v72, v73
	v_cvt_pk_bf16_f32 v96, v56, v57
	v_mfma_f32_32x32x16_bf16 v[134:149], v[174:177], v[84:87], v[134:149]
	v_exp_f32_e32 v77, v77
	v_exp_f32_e32 v61, v61
	v_add_f32_e32 v253, v76, v60
	v_add_f32_e32 v252, v252, v253
	v_cvt_pk_bf16_f32 v105, v74, v75
	v_cvt_pk_bf16_f32 v97, v58, v59
	v_mfma_f32_32x32x16_bf16 v[236:251], v[178:181], v[80:83], v[236:251]
	v_exp_f32_e32 v78, v78
	v_exp_f32_e32 v62, v62
	v_add_f32_e32 v253, v77, v61
	v_add_f32_e32 v252, v252, v253
	v_cvt_pk_bf16_f32 v106, v76, v77
	v_cvt_pk_bf16_f32 v98, v60, v61
	v_mfma_f32_32x32x16_bf16 v[134:149], v[182:185], v[80:83], v[134:149]
	v_exp_f32_e32 v79, v79
	v_exp_f32_e32 v63, v63
	v_add_f32_e32 v253, v78, v62
	v_add_f32_e32 v252, v252, v253
	v_add_f32_e32 v253, v79, v63
	v_add_f32_e32 v252, v252, v253
	v_cvt_pk_bf16_f32 v107, v78, v79
	v_cvt_pk_bf16_f32 v99, v62, v63
	v_add_f32_e32 v131, v131, v252
.Lmb3_A_tail:
	s_and_b32 s42, s98, 3
	s_cmp_eq_u32 s42, 0
	s_cbranch_scc1 .Lmb3_A_cin
	s_cmp_lg_u32 s98, s29
	s_cbranch_scc1 .Lmb3_A_nocin
.Lmb3_A_cin:
	s_lshr_b32 s42, s98, 2
	v_lshrrev_b32_e32 v219, s42, v129
	v_and_b32_e32 v219, 1, v219
	v_cmp_eq_u32_e32 vcc, 1, v219
	s_cmp_ge_i32 s98, s29
	s_nop 0
	v_cndmask_b32_e32 v219, v126, v128, vcc
	s_cselect_b64 vcc, 0, -1
	s_nop 1
	v_cndmask_b32_e32 v219, 0, v219, vcc
	v_add_f32_e32 v220, v0, v219
	v_add_f32_e32 v221, v1, v219
	v_add_f32_e32 v222, v2, v219
	v_add_f32_e32 v223, v3, v219
	v_add_f32_e32 v224, v4, v219
	v_add_f32_e32 v225, v5, v219
	v_add_f32_e32 v226, v6, v219
	v_add_f32_e32 v227, v7, v219
	v_add_f32_e32 v228, v8, v219
	v_add_f32_e32 v229, v9, v219
	v_add_f32_e32 v230, v10, v219
	v_add_f32_e32 v231, v11, v219
	v_add_f32_e32 v232, v12, v219
	v_add_f32_e32 v233, v13, v219
	v_add_f32_e32 v234, v14, v219
	v_add_f32_e32 v235, v15, v219
.Lmb3_A_nocin:
	v_lshl_add_u64 v[114:115], v[114:115], 0, s[20:21]
	v_subrev_u32_e32 v112, 64, v112
	v_lshl_add_u64 v[116:117], v[116:117], 0, s[20:21]
	s_add_i32 s30, s30, 1
	s_cmp_eq_u32 s37, 2
	s_cbranch_scc0 .Lmb3_A_wo
	s_waitcnt vmcnt(2) lgkmcnt(0)
.Lmb3_A_wd:
	s_cmp_lg_u32 s35, s34
	s_cbranch_scc0 .Lmb3_exitfix
	s_mov_b32 s43, s36
	s_add_i32 s35, s30, -1
	s_mov_b32 s37, 0
.Lmb3_B:
	s_barrier
	s_add_i32 s42, s35, 1
	s_cmp_ge_u32 s42, s28
	s_cbranch_scc1 .Lmb3_skKB
	s_add_i32 s42, s43, 0x2000
	s_and_b32 s42, s42, 0x6000
	s_add_i32 s42, s42, s74
	s_mov_b32 s99, m0
	s_mov_b32 m0, s42
	s_nop 0
	global_load_lds_dwordx4 v[114:115], off
	s_mov_b32 m0, s99
	s_mov_b32 s37, 1

.Lmb3_skVB:
	s_add_i32 s36, s43, 0x2000
	s_add_i32 s98, s43, 0x4000
	s_and_b32 s42, s98, 0x6000
	v_add_u32_e32 v133, s42, v130
	ds_read_b128 v[154:157], v133
	ds_read_b128 v[158:161], v133 offset:512
	ds_read_b128 v[162:165], v133 offset:2048
	ds_read_b128 v[166:169], v133 offset:2560
	ds_read_b128 v[170:173], v133 offset:4096
	ds_read_b128 v[174:177], v133 offset:4608
	ds_read_b128 v[178:181], v133 offset:6144
	ds_read_b128 v[182:185], v133 offset:6656
	s_and_b32 s42, s36, 0x6000
	v_add_u32_e32 v218, s42, v132
	s_add_i32 s98, s30, 2
	s_cmp_ge_i32 s30, s29
	s_cbranch_scc1 .Lmb3_B_near
	v_mfma_f32_32x32x16_bf16 v[16:31], v[108:111], v[186:189], v[16:31]
	v_exp_f32_e32 v236, v236
	v_exp_f32_e32 v134, v134
	v_mfma_f32_32x32x16_bf16 v[16:31], v[104:107], v[190:193], v[16:31]
	v_exp_f32_e32 v237, v237
	v_exp_f32_e32 v135, v135
	v_add_f32_e32 v252, v236, v134
	v_mfma_f32_32x32x16_bf16 v[16:31], v[100:103], v[194:197], v[16:31]
	v_exp_f32_e32 v238, v238
	v_exp_f32_e32 v136, v136
	v_add_f32_e32 v253, v237, v135
	v_add_f32_e32 v252, v252, v253
	v_mfma_f32_32x32x16_bf16 v[16:31], v[96:99], v[198:201], v[16:31]
	v_exp_f32_e32 v239, v239
	v_exp_f32_e32 v137, v137
	v_add_f32_e32 v253, v238, v136
	v_add_f32_e32 v252, v252, v253
	v_mfma_f32_32x32x16_bf16 v[32:47], v[108:111], v[202:205], v[32:47]
	v_exp_f32_e32 v240, v240
	v_exp_f32_e32 v138, v138
	v_add_f32_e32 v253, v239, v137
	v_add_f32_e32 v252, v252, v253
	ds_read_b64_tr_b16 v[186:187], v218
	ds_read_b64_tr_b16 v[188:189], v218 offset:512
	v_mfma_f32_32x32x16_bf16 v[32:47], v[104:107], v[206:209], v[32:47]
	v_exp_f32_e32 v241, v241
	v_exp_f32_e32 v139, v139
	v_add_f32_e32 v253, v240, v138
	v_add_f32_e32 v252, v252, v253
	ds_read_b64_tr_b16 v[190:191], v218 offset:1024
	ds_read_b64_tr_b16 v[192:193], v218 offset:1536
	v_mfma_f32_32x32x16_bf16 v[32:47], v[100:103], v[210:213], v[32:47]
	v_exp_f32_e32 v242, v242
	v_exp_f32_e32 v140, v140
	v_add_f32_e32 v253, v241, v139
	v_add_f32_e32 v252, v252, v253
	ds_read_b64_tr_b16 v[194:195], v218 offset:2048
	ds_read_b64_tr_b16 v[196:197], v218 offset:2560
	v_mfma_f32_32x32x16_bf16 v[32:47], v[96:99], v[214:217], v[32:47]
	v_exp_f32_e32 v243, v243
	v_exp_f32_e32 v141, v141
	v_add_f32_e32 v253, v242, v140
	v_add_f32_e32 v252, v252, v253
	ds_read_b64_tr_b16 v[198:199], v218 offset:3072
	ds_read_b64_tr_b16 v[200:201], v218 offset:3584
	s_waitcnt lgkmcnt(8)
	v_mfma_f32_32x32x16_bf16 v[64:79], v[154:157], v[92:95], v[220:235]
	v_exp_f32_e32 v244, v244
	v_exp_f32_e32 v142, v142
	v_add_f32_e32 v253, v243, v141
	v_add_f32_e32 v252, v252, v253
	v_cvt_pk_bf16_f32 v108, v236, v237
	v_cvt_pk_bf16_f32 v100, v134, v135
	ds_read_b64_tr_b16 v[202:203], v218 offset:4096
	ds_read_b64_tr_b16 v[204:205], v218 offset:4608
	v_mfma_f32_32x32x16_bf16 v[48:63], v[158:161], v[92:95], v[220:235]
	v_exp_f32_e32 v245, v245
	v_exp_f32_e32 v143, v143
	v_add_f32_e32 v253, v244, v142
	v_add_f32_e32 v252, v252, v253
	v_cvt_pk_bf16_f32 v109, v238, v239
	v_cvt_pk_bf16_f32 v101, v136, v137
	ds_read_b64_tr_b16 v[206:207], v218 offset:5120
	ds_read_b64_tr_b16 v[208:209], v218 offset:5632
	v_mfma_f32_32x32x16_bf16 v[64:79], v[162:165], v[88:91], v[64:79]
	v_exp_f32_e32 v246, v246
	v_exp_f32_e32 v144, v144
	v_add_f32_e32 v253, v245, v143
	v_add_f32_e32 v252, v252, v253
	v_cvt_pk_bf16_f32 v110, v240, v241
	v_cvt_pk_bf16_f32 v102, v138, v139
	ds_read_b64_tr_b16 v[210:211], v218 offset:6144
	ds_read_b64_tr_b16 v[212:213], v218 offset:6656
	v_mfma_f32_32x32x16_bf16 v[48:63], v[166:169], v[88:91], v[48:63]
	v_exp_f32_e32 v247, v247
	v_exp_f32_e32 v145, v145
	v_add_f32_e32 v253, v246, v144
	v_add_f32_e32 v252, v252, v253
	v_cvt_pk_bf16_f32 v111, v242, v243
	v_cvt_pk_bf16_f32 v103, v140, v141
	ds_read_b64_tr_b16 v[214:215], v218 offset:7168
	ds_read_b64_tr_b16 v[216:217], v218 offset:7680
	v_mfma_f32_32x32x16_bf16 v[64:79], v[170:173], v[84:87], v[64:79]
	v_exp_f32_e32 v248, v248
	v_exp_f32_e32 v146, v146
	v_add_f32_e32 v253, v247, v145
	v_add_f32_e32 v252, v252, v253
	v_cvt_pk_bf16_f32 v104, v244, v245
	v_cvt_pk_bf16_f32 v96, v142, v143
	v_mfma_f32_32x32x16_bf16 v[48:63], v[174:177], v[84:87], v[48:63]
	v_exp_f32_e32 v249, v249
	v_exp_f32_e32 v147, v147
	v_add_f32_e32 v253, v248, v146
	v_add_f32_e32 v252, v252, v253
	v_cvt_pk_bf16_f32 v105, v246, v247
	v_cvt_pk_bf16_f32 v97, v144, v145
	v_mfma_f32_32x32x16_bf16 v[64:79], v[178:181], v[80:83], v[64:79]
	v_exp_f32_e32 v250, v250
	v_exp_f32_e32 v148, v148
	v_add_f32_e32 v253, v249, v147
	v_add_f32_e32 v252, v252, v253
	v_cvt_pk_bf16_f32 v106, v248, v249
	v_cvt_pk_bf16_f32 v98, v146, v147
	v_mfma_f32_32x32x16_bf16 v[48:63], v[182:185], v[80:83], v[48:63]
	v_exp_f32_e32 v251, v251
	v_exp_f32_e32 v149, v149
	v_add_f32_e32 v253, v250, v148
	v_add_f32_e32 v252, v252, v253
	v_add_f32_e32 v253, v251, v149
	v_add_f32_e32 v252, v252, v253
	v_cvt_pk_bf16_f32 v107, v250, v251
	v_cvt_pk_bf16_f32 v99, v148, v149
	v_add_f32_e32 v131, v131, v252

; template <int MODE> __device__ __forceinline__ void attn_unit(int b, int h, int qb, int t_lo, const bf16_t* Q, const bf16_t* __restrict__ K, const bf16_t* __restrict__ V, bf16_t* O, ATT_LAS unsigned char* lds, const int wid, const float kn2, const float bmax) {
;     ...
; #pragma unroll 1
;     for (int j = 0; j < n - 1; ++j) ATT_ITER(j, true, true);
;     ATT_ITER(n - 1, false, true);
.Lmb3_B_wd:
	s_cmp_lg_u32 s35, s34
	s_cbranch_scc0 .Lmb3_exitfix
	s_mov_b32 s43, s36
	s_add_i32 s35, s30, -1
	s_mov_b32 s37, 0
	s_branch .Lmb3_A
.Lmb3_A_near:
	s_waitcnt lgkmcnt(8)
	v_mfma_f32_32x32x16_bf16 v[16:31], v[108:111], v[186:189], v[16:31]
	v_mfma_f32_32x32x16_bf16 v[16:31], v[104:107], v[190:193], v[16:31]
	v_mfma_f32_32x32x16_bf16 v[16:31], v[100:103], v[194:197], v[16:31]
	v_mfma_f32_32x32x16_bf16 v[16:31], v[96:99], v[198:201], v[16:31]
	v_mfma_f32_32x32x16_bf16 v[32:47], v[108:111], v[202:205], v[32:47]
	v_mfma_f32_32x32x16_bf16 v[32:47], v[104:107], v[206:209], v[32:47]
	v_mfma_f32_32x32x16_bf16 v[32:47], v[100:103], v[210:213], v[32:47]
	v_mfma_f32_32x32x16_bf16 v[32:47], v[96:99], v[214:217], v[32:47]
	s_lshr_b32 s42, s30, 2
	s_cmp_eq_u32 s42, s93
	s_cselect_b64 s[10:11], -1, 0
	s_lshl_b32 s42, 1, s42
	v_and_b32_e32 v96, s42, v129
	v_cmp_ne_u32_e32 vcc, 0, v96
	s_or_b64 vcc, s[10:11], vcc
	s_nop 0
	v_cndmask_b32_e32 v96, v127, v112, vcc
	v_lshl_add_u32 v96, v96, 2, 0
	v_add_u32_e32 v104, 0x1d000, v96
	ds_read2_b32 v[96:97], v104 offset0:58 offset1:59
	ds_read2_b32 v[98:99], v104 offset0:26 offset1:27
	ds_read2_b32 v[100:101], v104 offset0:56 offset1:57
	s_waitcnt lgkmcnt(2)
	v_pk_add_f32 v[64:65], v[64:65], v[96:97] op_sel:[0,1] op_sel_hi:[1,0]
	ds_read2_b32 v[96:97], v104 offset0:24 offset1:25
	s_waitcnt lgkmcnt(2)
	v_pk_add_f32 v[48:49], v[48:49], v[98:99] op_sel:[0,1] op_sel_hi:[1,0]
	ds_read2_b32 v[98:99], v104 offset0:50 offset1:51
	s_waitcnt lgkmcnt(2)
	v_pk_add_f32 v[66:67], v[66:67], v[100:101] op_sel:[0,1] op_sel_hi:[1,0]
	ds_read2_b32 v[100:101], v104 offset0:18 offset1:19
	s_waitcnt lgkmcnt(1)
	v_pk_add_f32 v[68:69], v[68:69], v[98:99] op_sel:[0,1] op_sel_hi:[1,0]
	ds_read2_b32 v[98:99], v104 offset0:16 offset1:17
	s_waitcnt lgkmcnt(1)
	v_pk_add_f32 v[52:53], v[52:53], v[100:101] op_sel:[0,1] op_sel_hi:[1,0]
	ds_read2_b32 v[100:101], v104 offset0:42 offset1:43
	v_pk_add_f32 v[50:51], v[50:51], v[96:97] op_sel:[0,1] op_sel_hi:[1,0]
	ds_read2_b32 v[96:97], v104 offset0:48 offset1:49
	s_waitcnt lgkmcnt(1)
	v_pk_add_f32 v[72:73], v[72:73], v[100:101] op_sel:[0,1] op_sel_hi:[1,0]
	ds_read2_b32 v[100:101], v104 offset0:8 offset1:9
	s_waitcnt lgkmcnt(1)
	v_pk_add_f32 v[70:71], v[70:71], v[96:97] op_sel:[0,1] op_sel_hi:[1,0]
	ds_read2_b32 v[96:97], v104 offset0:10 offset1:11
	v_pk_add_f32 v[54:55], v[54:55], v[98:99] op_sel:[0,1] op_sel_hi:[1,0]
	ds_read2_b32 v[98:99], v104 offset0:40 offset1:41
	s_waitcnt lgkmcnt(2)
	v_pk_add_f32 v[58:59], v[58:59], v[100:101] op_sel:[0,1] op_sel_hi:[1,0]
	s_waitcnt lgkmcnt(1)
	v_pk_add_f32 v[56:57], v[56:57], v[96:97] op_sel:[0,1] op_sel_hi:[1,0]
	ds_read2_b32 v[96:97], v104 offset0:34 offset1:35
	s_waitcnt lgkmcnt(1)
	v_pk_add_f32 v[74:75], v[74:75], v[98:99] op_sel:[0,1] op_sel_hi:[1,0]
	ds_read2_b32 v[98:99], v104 offset0:2 offset1:3
	ds_read2_b32 v[102:103], v104 offset0:32 offset1:33
	ds_read2_b32 v[104:105], v104 offset1:1
	s_waitcnt lgkmcnt(3)
	v_pk_add_f32 v[76:77], v[76:77], v[96:97] op_sel:[0,1] op_sel_hi:[1,0]
	s_waitcnt lgkmcnt(2)
	v_pk_add_f32 v[60:61], v[60:61], v[98:99] op_sel:[0,1] op_sel_hi:[1,0]
	s_waitcnt lgkmcnt(1)
	v_pk_add_f32 v[78:79], v[78:79], v[102:103] op_sel:[0,1] op_sel_hi:[1,0]
	s_waitcnt lgkmcnt(0)
	v_pk_add_f32 v[62:63], v[62:63], v[104:105] op_sel:[0,1] op_sel_hi:[1,0]
	s_waitcnt lgkmcnt(0)
	v_mfma_f32_32x32x16_bf16 v[236:251], v[154:157], v[92:95], v[220:235]
	ds_read_b64_tr_b16 v[186:187], v218
	ds_read_b64_tr_b16 v[188:189], v218 offset:512
	ds_read_b64_tr_b16 v[190:191], v218 offset:1024
	ds_read_b64_tr_b16 v[192:193], v218 offset:1536
	ds_read_b64_tr_b16 v[194:195], v218 offset:2048
	ds_read_b64_tr_b16 v[196:197], v218 offset:2560
	ds_read_b64_tr_b16 v[198:199], v218 offset:3072
	ds_read_b64_tr_b16 v[200:201], v218 offset:3584
	ds_read_b64_tr_b16 v[202:203], v218 offset:4096
	ds_read_b64_tr_b16 v[204:205], v218 offset:4608
	ds_read_b64_tr_b16 v[206:207], v218 offset:5120
	v_mfma_f32_32x32x16_bf16 v[134:149], v[158:161], v[92:95], v[220:235]
	ds_read_b64_tr_b16 v[208:209], v218 offset:5632
	ds_read_b64_tr_b16 v[210:211], v218 offset:6144
	ds_read_b64_tr_b16 v[212:213], v218 offset:6656
	ds_read_b64_tr_b16 v[214:215], v218 offset:7168
	ds_read_b64_tr_b16 v[216:217], v218 offset:7680
	v_exp_f32_e32 v64, v64
	v_exp_f32_e32 v48, v48
	v_exp_f32_e32 v65, v65
	v_exp_f32_e32 v49, v49
	v_exp_f32_e32 v66, v66
	v_exp_f32_e32 v50, v50
	v_mfma_f32_32x32x16_bf16 v[236:251], v[162:165], v[88:91], v[236:251]
	v_exp_f32_e32 v67, v67
	v_exp_f32_e32 v51, v51
	v_add_f32_e32 v252, v48, v64
	v_exp_f32_e32 v68, v68
	v_exp_f32_e32 v52, v52
	v_add_f32_e32 v252, 0, v252
	v_add_f32_e32 v253, v49, v65
	v_exp_f32_e32 v69, v69
	v_exp_f32_e32 v53, v53
	v_add_f32_e32 v252, v253, v252
	v_add_f32_e32 v253, v50, v66
	v_mfma_f32_32x32x16_bf16 v[134:149], v[166:169], v[88:91], v[134:149]
	v_exp_f32_e32 v70, v70
	v_exp_f32_e32 v54, v54
	v_add_f32_e32 v252, v253, v252
	v_add_f32_e32 v253, v51, v67
	v_exp_f32_e32 v71, v71
	v_exp_f32_e32 v55, v55
	v_add_f32_e32 v252, v253, v252
	v_add_f32_e32 v253, v52, v68
	v_exp_f32_e32 v72, v72
	v_exp_f32_e32 v56, v56
	v_add_f32_e32 v252, v253, v252
	v_mfma_f32_32x32x16_bf16 v[236:251], v[170:173], v[84:87], v[236:251]
	v_add_f32_e32 v253, v53, v69
	v_exp_f32_e32 v73, v73
	v_exp_f32_e32 v57, v57
	v_add_f32_e32 v252, v253, v252
	v_add_f32_e32 v253, v54, v70
	v_exp_f32_e32 v74, v74
	v_exp_f32_e32 v58, v58
	v_add_f32_e32 v252, v253, v252
	v_add_f32_e32 v253, v55, v71
	v_exp_f32_e32 v75, v75
	v_exp_f32_e32 v59, v59
	v_mfma_f32_32x32x16_bf16 v[134:149], v[174:177], v[84:87], v[134:149]
	v_add_f32_e32 v252, v253, v252
	v_add_f32_e32 v253, v56, v72
	v_exp_f32_e32 v76, v76
	v_exp_f32_e32 v60, v60
	v_add_f32_e32 v252, v253, v252
	v_add_f32_e32 v253, v57, v73
	v_exp_f32_e32 v77, v77
	v_exp_f32_e32 v61, v61
	v_add_f32_e32 v252, v253, v252
	v_add_f32_e32 v253, v58, v74
	v_exp_f32_e32 v78, v78
	v_mfma_f32_32x32x16_bf16 v[236:251], v[178:181], v[80:83], v[236:251]
	v_exp_f32_e32 v62, v62
	v_add_f32_e32 v252, v253, v252
	v_add_f32_e32 v253, v59, v75
	v_exp_f32_e32 v79, v79
	v_exp_f32_e32 v63, v63
	v_add_f32_e32 v252, v253, v252
	v_add_f32_e32 v253, v60, v76
	v_add_f32_e32 v252, v253, v252
	v_add_f32_e32 v253, v61, v77
	v_add_f32_e32 v252, v253, v252
	v_add_f32_e32 v253, v62, v78
	v_mfma_f32_32x32x16_bf16 v[134:149], v[182:185], v[80:83], v[134:149]
	v_add_f32_e32 v252, v253, v252
	v_add_f32_e32 v253, v63, v79
	v_add_f32_e32 v252, v253, v252
	v_add_f32_e32 v131, v131, v252
	v_cvt_pk_bf16_f32 v108, v64, v65
	v_cvt_pk_bf16_f32 v109, v66, v67
	v_cvt_pk_bf16_f32 v110, v68, v69
	v_cvt_pk_bf16_f32 v111, v70, v71
	v_cvt_pk_bf16_f32 v104, v72, v73
	v_cvt_pk_bf16_f32 v105, v74, v75
	v_cvt_pk_bf16_f32 v106, v76, v77
	v_cvt_pk_bf16_f32 v107, v78, v79
	v_cvt_pk_bf16_f32 v100, v48, v49
	v_cvt_pk_bf16_f32 v101, v50, v51
	v_cvt_pk_bf16_f32 v102, v52, v53
	v_cvt_pk_bf16_f32 v103, v54, v55
	v_cvt_pk_bf16_f32 v96, v56, v57
	v_cvt_pk_bf16_f32 v97, v58, v59
	v_cvt_pk_bf16_f32 v98, v60, v61
	v_cvt_pk_bf16_f32 v99, v62, v63
	s_branch .Lmb3_A_tail
.Lmb3_A_wo:
	s_cmp_eq_u32 s37, 1
	s_cbranch_scc1 .Lmb3_A_w1
	s_waitcnt vmcnt(0) lgkmcnt(0)
	s_branch .Lmb3_A_wd

.Lmb3_B_near:
	s_waitcnt lgkmcnt(8)
	v_mfma_f32_32x32x16_bf16 v[16:31], v[108:111], v[186:189], v[16:31]
	v_mfma_f32_32x32x16_bf16 v[16:31], v[104:107], v[190:193], v[16:31]
	v_mfma_f32_32x32x16_bf16 v[16:31], v[100:103], v[194:197], v[16:31]
	v_mfma_f32_32x32x16_bf16 v[16:31], v[96:99], v[198:201], v[16:31]
	v_mfma_f32_32x32x16_bf16 v[32:47], v[108:111], v[202:205], v[32:47]
	v_mfma_f32_32x32x16_bf16 v[32:47], v[104:107], v[206:209], v[32:47]
	v_mfma_f32_32x32x16_bf16 v[32:47], v[100:103], v[210:213], v[32:47]
	v_mfma_f32_32x32x16_bf16 v[32:47], v[96:99], v[214:217], v[32:47]
	s_lshr_b32 s42, s30, 2
	s_cmp_eq_u32 s42, s93
	s_cselect_b64 s[10:11], -1, 0
	s_lshl_b32 s42, 1, s42
	v_and_b32_e32 v96, s42, v129
	v_cmp_ne_u32_e32 vcc, 0, v96
	s_or_b64 vcc, s[10:11], vcc
	s_nop 0
	v_cndmask_b32_e32 v96, v127, v112, vcc
	v_lshl_add_u32 v96, v96, 2, 0
	v_add_u32_e32 v104, 0x1d000, v96
	ds_read2_b32 v[96:97], v104 offset0:58 offset1:59
	ds_read2_b32 v[98:99], v104 offset0:26 offset1:27
	ds_read2_b32 v[100:101], v104 offset0:56 offset1:57
	s_waitcnt lgkmcnt(2)
	v_pk_add_f32 v[236:237], v[236:237], v[96:97] op_sel:[0,1] op_sel_hi:[1,0]
	ds_read2_b32 v[96:97], v104 offset0:24 offset1:25
	s_waitcnt lgkmcnt(2)
	v_pk_add_f32 v[134:135], v[134:135], v[98:99] op_sel:[0,1] op_sel_hi:[1,0]
	ds_read2_b32 v[98:99], v104 offset0:50 offset1:51
	s_waitcnt lgkmcnt(2)
	v_pk_add_f32 v[238:239], v[238:239], v[100:101] op_sel:[0,1] op_sel_hi:[1,0]
	ds_read2_b32 v[100:101], v104 offset0:18 offset1:19
	s_waitcnt lgkmcnt(1)
	v_pk_add_f32 v[240:241], v[240:241], v[98:99] op_sel:[0,1] op_sel_hi:[1,0]
	ds_read2_b32 v[98:99], v104 offset0:16 offset1:17
	s_waitcnt lgkmcnt(1)
	v_pk_add_f32 v[138:139], v[138:139], v[100:101] op_sel:[0,1] op_sel_hi:[1,0]
	ds_read2_b32 v[100:101], v104 offset0:42 offset1:43
	v_pk_add_f32 v[136:137], v[136:137], v[96:97] op_sel:[0,1] op_sel_hi:[1,0]
	ds_read2_b32 v[96:97], v104 offset0:48 offset1:49
	s_waitcnt lgkmcnt(1)
	v_pk_add_f32 v[244:245], v[244:245], v[100:101] op_sel:[0,1] op_sel_hi:[1,0]
	ds_read2_b32 v[100:101], v104 offset0:8 offset1:9
	s_waitcnt lgkmcnt(1)
	v_pk_add_f32 v[242:243], v[242:243], v[96:97] op_sel:[0,1] op_sel_hi:[1,0]
	ds_read2_b32 v[96:97], v104 offset0:10 offset1:11
	v_pk_add_f32 v[140:141], v[140:141], v[98:99] op_sel:[0,1] op_sel_hi:[1,0]
	ds_read2_b32 v[98:99], v104 offset0:40 offset1:41
	s_waitcnt lgkmcnt(2)
	v_pk_add_f32 v[144:145], v[144:145], v[100:101] op_sel:[0,1] op_sel_hi:[1,0]
	s_waitcnt lgkmcnt(1)
	v_pk_add_f32 v[142:143], v[142:143], v[96:97] op_sel:[0,1] op_sel_hi:[1,0]
	ds_read2_b32 v[96:97], v104 offset0:34 offset1:35
	s_waitcnt lgkmcnt(1)
	v_pk_add_f32 v[246:247], v[246:247], v[98:99] op_sel:[0,1] op_sel_hi:[1,0]
	ds_read2_b32 v[98:99], v104 offset0:2 offset1:3
	ds_read2_b32 v[102:103], v104 offset0:32 offset1:33
	ds_read2_b32 v[104:105], v104 offset1:1
	s_waitcnt lgkmcnt(3)
	v_pk_add_f32 v[248:249], v[248:249], v[96:97] op_sel:[0,1] op_sel_hi:[1,0]
	s_waitcnt lgkmcnt(2)
	v_pk_add_f32 v[146:147], v[146:147], v[98:99] op_sel:[0,1] op_sel_hi:[1,0]
	s_waitcnt lgkmcnt(1)
	v_pk_add_f32 v[250:251], v[250:251], v[102:103] op_sel:[0,1] op_sel_hi:[1,0]
	s_waitcnt lgkmcnt(0)
	v_pk_add_f32 v[148:149], v[148:149], v[104:105] op_sel:[0,1] op_sel_hi:[1,0]
	s_waitcnt lgkmcnt(0)
	v_mfma_f32_32x32x16_bf16 v[64:79], v[154:157], v[92:95], v[220:235]
	ds_read_b64_tr_b16 v[186:187], v218
	ds_read_b64_tr_b16 v[188:189], v218 offset:512
	ds_read_b64_tr_b16 v[190:191], v218 offset:1024
	ds_read_b64_tr_b16 v[192:193], v218 offset:1536
	ds_read_b64_tr_b16 v[194:195], v218 offset:2048
	ds_read_b64_tr_b16 v[196:197], v218 offset:2560
	ds_read_b64_tr_b16 v[198:199], v218 offset:3072
	ds_read_b64_tr_b16 v[200:201], v218 offset:3584
	ds_read_b64_tr_b16 v[202:203], v218 offset:4096
	ds_read_b64_tr_b16 v[204:205], v218 offset:4608
	ds_read_b64_tr_b16 v[206:207], v218 offset:5120
	v_mfma_f32_32x32x16_bf16 v[48:63], v[158:161], v[92:95], v[220:235]
	ds_read_b64_tr_b16 v[208:209], v218 offset:5632
	ds_read_b64_tr_b16 v[210:211], v218 offset:6144
	ds_read_b64_tr_b16 v[212:213], v218 offset:6656
	ds_read_b64_tr_b16 v[214:215], v218 offset:7168
	ds_read_b64_tr_b16 v[216:217], v218 offset:7680
	v_exp_f32_e32 v236, v236
	v_exp_f32_e32 v134, v134
	v_exp_f32_e32 v237, v237
	v_exp_f32_e32 v135, v135
	v_exp_f32_e32 v238, v238
	v_exp_f32_e32 v136, v136
	v_mfma_f32_32x32x16_bf16 v[64:79], v[162:165], v[88:91], v[64:79]
	v_exp_f32_e32 v239, v239
	v_exp_f32_e32 v137, v137
	v_add_f32_e32 v252, v134, v236
	v_exp_f32_e32 v240, v240
	v_exp_f32_e32 v138, v138
	v_add_f32_e32 v252, 0, v252
	v_add_f32_e32 v253, v135, v237
	v_exp_f32_e32 v241, v241
	v_exp_f32_e32 v139, v139
	v_add_f32_e32 v252, v253, v252
	v_add_f32_e32 v253, v136, v238
	v_mfma_f32_32x32x16_bf16 v[48:63], v[166:169], v[88:91], v[48:63]
	v_exp_f32_e32 v242, v242
	v_exp_f32_e32 v140, v140
	v_add_f32_e32 v252, v253, v252
	v_add_f32_e32 v253, v137, v239
	v_exp_f32_e32 v243, v243
	v_exp_f32_e32 v141, v141
	v_add_f32_e32 v252, v253, v252
	v_add_f32_e32 v253, v138, v240
	v_exp_f32_e32 v244, v244
	v_exp_f32_e32 v142, v142
	v_add_f32_e32 v252, v253, v252
	v_mfma_f32_32x32x16_bf16 v[64:79], v[170:173], v[84:87], v[64:79]
	v_add_f32_e32 v253, v139, v241
	v_exp_f32_e32 v245, v245
	v_exp_f32_e32 v143, v143
	v_add_f32_e32 v252, v253, v252
	v_add_f32_e32 v253, v140, v242
	v_exp_f32_e32 v246, v246
	v_exp_f32_e32 v144, v144
	v_add_f32_e32 v252, v253, v252
	v_add_f32_e32 v253, v141, v243
	v_exp_f32_e32 v247, v247
	v_exp_f32_e32 v145, v145
	v_mfma_f32_32x32x16_bf16 v[48:63], v[174:177], v[84:87], v[48:63]
	v_add_f32_e32 v252, v253, v252
	v_add_f32_e32 v253, v142, v244
	v_exp_f32_e32 v248, v248
	v_exp_f32_e32 v146, v146
	v_add_f32_e32 v252, v253, v252
	v_add_f32_e32 v253, v143, v245
	v_exp_f32_e32 v249, v249
	v_exp_f32_e32 v147, v147
	v_add_f32_e32 v252, v253, v252
	v_add_f32_e32 v253, v144, v246
	v_exp_f32_e32 v250, v250
	v_mfma_f32_32x32x16_bf16 v[64:79], v[178:181], v[80:83], v[64:79]
	v_exp_f32_e32 v148, v148
	v_add_f32_e32 v252, v253, v252
	v_add_f32_e32 v253, v145, v247
	v_exp_f32_e32 v251, v251
	v_exp_f32_e32 v149, v149
	v_add_f32_e32 v252, v253, v252
	v_add_f32_e32 v253, v146, v248
	v_add_f32_e32 v252, v253, v252
	v_add_f32_e32 v253, v147, v249
	v_add_f32_e32 v252, v253, v252
	v_add_f32_e32 v253, v148, v250
	v_mfma_f32_32x32x16_bf16 v[48:63], v[182:185], v[80:83], v[48:63]
	v_add_f32_e32 v252, v253, v252
	v_add_f32_e32 v253, v149, v251
	v_add_f32_e32 v252, v253, v252
	v_add_f32_e32 v131, v131, v252
	v_cvt_pk_bf16_f32 v108, v236, v237
	v_cvt_pk_bf16_f32 v109, v238, v239
	v_cvt_pk_bf16_f32 v110, v240, v241
	v_cvt_pk_bf16_f32 v111, v242, v243
	v_cvt_pk_bf16_f32 v104, v244, v245
	v_cvt_pk_bf16_f32 v105, v246, v247
	v_cvt_pk_bf16_f32 v106, v248, v249
	v_cvt_pk_bf16_f32 v107, v250, v251
	v_cvt_pk_bf16_f32 v100, v134, v135
	v_cvt_pk_bf16_f32 v101, v136, v137
	v_cvt_pk_bf16_f32 v102, v138, v139
	v_cvt_pk_bf16_f32 v103, v140, v141
	v_cvt_pk_bf16_f32 v96, v142, v143
	v_cvt_pk_bf16_f32 v97, v144, v145
	v_cvt_pk_bf16_f32 v98, v146, v147
	v_cvt_pk_bf16_f32 v99, v148, v149
	s_branch .Lmb3_B_tail
